# residual-GEMM epilogue: second half's x rows prefetched into retired accumulator blocks
# baseline (speedup 1.0000x reference)
.Lgm_f2_join:
	s_waitcnt lgkmcnt(13)
	v_mfma_f32_16x16x32_bf16 v[4:7], v[100:103], v[124:127], v[4:7]
	v_mfma_f32_16x16x32_bf16 v[20:23], v[104:107], v[124:127], v[20:23]
	v_mfma_f32_16x16x32_bf16 v[36:39], v[108:111], v[124:127], v[36:39]
	v_mfma_f32_16x16x32_bf16 v[52:55], v[112:115], v[124:127], v[52:55]
	v_mfma_f32_16x16x32_bf16 v[68:71], v[116:119], v[124:127], v[68:71]
	v_mfma_f32_16x16x32_bf16 v[84:87], v[120:123], v[124:127], v[84:87]
	s_waitcnt lgkmcnt(12)
	v_mfma_f32_16x16x32_bf16 v[8:11], v[100:103], v[128:131], v[8:11]
	v_mfma_f32_16x16x32_bf16 v[24:27], v[104:107], v[128:131], v[24:27]
	v_mfma_f32_16x16x32_bf16 v[40:43], v[108:111], v[128:131], v[40:43]
	v_mfma_f32_16x16x32_bf16 v[56:59], v[112:115], v[128:131], v[56:59]
	v_mfma_f32_16x16x32_bf16 v[72:75], v[116:119], v[128:131], v[72:75]
	v_mfma_f32_16x16x32_bf16 v[88:91], v[120:123], v[128:131], v[88:91]
	s_waitcnt lgkmcnt(11)
	v_mfma_f32_16x16x32_bf16 v[12:15], v[100:103], v[132:135], v[12:15]
	v_mfma_f32_16x16x32_bf16 v[28:31], v[104:107], v[132:135], v[28:31]
	v_mfma_f32_16x16x32_bf16 v[44:47], v[108:111], v[132:135], v[44:47]
	v_mfma_f32_16x16x32_bf16 v[60:63], v[112:115], v[132:135], v[60:63]
	v_mfma_f32_16x16x32_bf16 v[76:79], v[116:119], v[132:135], v[76:79]
	v_mfma_f32_16x16x32_bf16 v[92:95], v[120:123], v[132:135], v[92:95]
	s_waitcnt lgkmcnt(10)
	v_mfma_f32_16x16x32_bf16 v[16:19], v[100:103], v[136:139], v[16:19]
	v_mfma_f32_16x16x32_bf16 v[32:35], v[104:107], v[136:139], v[32:35]
	v_mfma_f32_16x16x32_bf16 v[48:51], v[108:111], v[136:139], v[48:51]
	v_mfma_f32_16x16x32_bf16 v[64:67], v[112:115], v[136:139], v[64:67]
	v_mfma_f32_16x16x32_bf16 v[80:83], v[116:119], v[136:139], v[80:83]
	v_mfma_f32_16x16x32_bf16 v[96:99], v[120:123], v[136:139], v[96:99]
	s_waitcnt lgkmcnt(0)
	s_add_u32 s34, s34, 1
	s_add_u32 s31, s31, 1
	s_cmp_lt_u32 s34, 64
	s_cbranch_scc1 .Lgm_f2_rot
	v_mfma_f32_16x16x32_bf16 v[4:7], v[140:143], v[164:167], v[4:7]
	v_mfma_f32_16x16x32_bf16 v[20:23], v[144:147], v[164:167], v[20:23]
	v_mfma_f32_16x16x32_bf16 v[36:39], v[148:151], v[164:167], v[36:39]
	v_mfma_f32_16x16x32_bf16 v[52:55], v[152:155], v[164:167], v[52:55]
	v_mfma_f32_16x16x32_bf16 v[68:71], v[156:159], v[164:167], v[68:71]
	v_mfma_f32_16x16x32_bf16 v[84:87], v[160:163], v[164:167], v[84:87]
	v_mfma_f32_16x16x32_bf16 v[8:11], v[140:143], v[168:171], v[8:11]
	v_mfma_f32_16x16x32_bf16 v[24:27], v[144:147], v[168:171], v[24:27]
	v_mfma_f32_16x16x32_bf16 v[40:43], v[148:151], v[168:171], v[40:43]
	v_mfma_f32_16x16x32_bf16 v[56:59], v[152:155], v[168:171], v[56:59]
	v_mfma_f32_16x16x32_bf16 v[72:75], v[156:159], v[168:171], v[72:75]
	v_mfma_f32_16x16x32_bf16 v[88:91], v[160:163], v[168:171], v[88:91]
	v_mfma_f32_16x16x32_bf16 v[12:15], v[140:143], v[172:175], v[12:15]
	v_mfma_f32_16x16x32_bf16 v[28:31], v[144:147], v[172:175], v[28:31]
	v_mfma_f32_16x16x32_bf16 v[44:47], v[148:151], v[172:175], v[44:47]
	v_mfma_f32_16x16x32_bf16 v[60:63], v[152:155], v[172:175], v[60:63]
	v_mfma_f32_16x16x32_bf16 v[76:79], v[156:159], v[172:175], v[76:79]
	v_mfma_f32_16x16x32_bf16 v[92:95], v[160:163], v[172:175], v[92:95]
	v_mfma_f32_16x16x32_bf16 v[16:19], v[140:143], v[176:179], v[16:19]
	v_mfma_f32_16x16x32_bf16 v[32:35], v[144:147], v[176:179], v[32:35]
	v_mfma_f32_16x16x32_bf16 v[48:51], v[148:151], v[176:179], v[48:51]
	v_mfma_f32_16x16x32_bf16 v[64:67], v[152:155], v[176:179], v[64:67]
	v_mfma_f32_16x16x32_bf16 v[80:83], v[156:159], v[176:179], v[80:83]
	v_mfma_f32_16x16x32_bf16 v[96:99], v[160:163], v[176:179], v[96:99]
	s_and_b32 s6, s35, 31
	s_mul_i32 s6, s6, 192
	s_lshr_b32 s7, s35, 5
	s_lshl_b32 s7, s7, 7
	s_nop 7
	s_mul_i32 s4, s6, 0x1000
	s_lshl_b32 s5, s7, 2
	s_add_u32 s4, s4, s5
	v_add_u32_e32 v197, s4, v205
	v_add_u32_e32 v192, s6, v190
	v_lshl_add_u32 v193, s7, 2, v191
	s_sub_i32 s4, s6, 0xc00
	s_max_i32 s4, s4, 0
	s_lshr_b32 s4, s4, 10
	s_add_i32 s5, s6, -2881
	s_max_i32 s5, s5, 0
	s_lshr_b32 s5, s5, 10
	s_movk_i32 s7, 0x1400
	s_cmp_eq_u32 s4, 0
	s_cselect_b32 s7, 0x1000, s7
	s_mul_i32 s4, s4, 0x6000
	s_mul_i32 s5, s5, 0x6000
	v_mov_b32_e32 v194, v197
	v_add_u32_e32 v195, 0, v192
	v_cmp_gt_u32_e32 vcc, 0x1000, v195
	v_mov_b32_e32 v0, s98
	v_mov_b32_e32 v1, s99
	v_mov_b32_e32 v3, s58
	v_cndmask_b32_e32 v0, v0, v3, vcc
	v_mov_b32_e32 v3, s59
	v_cndmask_b32_e32 v1, v1, v3, vcc
	v_add_co_u32_e32 v0, vcc, v0, v194
	s_nop 1
	v_addc_co_u32_e32 v1, vcc, 0, v1, vcc
	global_load_dwordx4 v[100:103], v[0:1], off
	v_add_u32_e32 v194, 0x4000, v194
	v_add_u32_e32 v195, 4, v192
	v_cmp_gt_u32_e32 vcc, 0x1000, v195
	v_mov_b32_e32 v0, s98
	v_mov_b32_e32 v1, s99
	v_mov_b32_e32 v3, s58
	v_cndmask_b32_e32 v0, v0, v3, vcc
	v_mov_b32_e32 v3, s59
	v_cndmask_b32_e32 v1, v1, v3, vcc
	v_add_co_u32_e32 v0, vcc, v0, v194
	s_nop 1
	v_addc_co_u32_e32 v1, vcc, 0, v1, vcc
	global_load_dwordx4 v[104:107], v[0:1], off
	v_add_u32_e32 v194, 0x4000, v194
	v_add_u32_e32 v195, 8, v192
	v_cmp_gt_u32_e32 vcc, 0x1000, v195
	v_mov_b32_e32 v0, s98
	v_mov_b32_e32 v1, s99
	v_mov_b32_e32 v3, s58
	v_cndmask_b32_e32 v0, v0, v3, vcc
	v_mov_b32_e32 v3, s59
	v_cndmask_b32_e32 v1, v1, v3, vcc
	v_add_co_u32_e32 v0, vcc, v0, v194
	s_nop 1
	v_addc_co_u32_e32 v1, vcc, 0, v1, vcc
	global_load_dwordx4 v[108:111], v[0:1], off
	v_add_u32_e32 v194, 0x4000, v194
	v_add_u32_e32 v195, 12, v192
	v_cmp_gt_u32_e32 vcc, 0x1000, v195
	v_mov_b32_e32 v0, s98
	v_mov_b32_e32 v1, s99
	v_mov_b32_e32 v3, s58
	v_cndmask_b32_e32 v0, v0, v3, vcc
	v_mov_b32_e32 v3, s59
	v_cndmask_b32_e32 v1, v1, v3, vcc
	v_add_co_u32_e32 v0, vcc, v0, v194
	s_nop 1
	v_addc_co_u32_e32 v1, vcc, 0, v1, vcc
	global_load_dwordx4 v[112:115], v[0:1], off
	v_add_u32_e32 v194, 0x4000, v194
	v_add_u32_e32 v195, 16, v192
	v_cmp_gt_u32_e32 vcc, 0x1000, v195
	v_mov_b32_e32 v0, s98
	v_mov_b32_e32 v1, s99
	v_mov_b32_e32 v3, s58
	v_cndmask_b32_e32 v0, v0, v3, vcc
	v_mov_b32_e32 v3, s59
	v_cndmask_b32_e32 v1, v1, v3, vcc
	v_add_co_u32_e32 v0, vcc, v0, v194
	s_nop 1
	v_addc_co_u32_e32 v1, vcc, 0, v1, vcc
	global_load_dwordx4 v[116:119], v[0:1], off
	v_add_u32_e32 v194, 0x4000, v194
	v_add_u32_e32 v195, 20, v192
	v_cmp_gt_u32_e32 vcc, 0x1000, v195
	v_mov_b32_e32 v0, s98
	v_mov_b32_e32 v1, s99
	v_mov_b32_e32 v3, s58
	v_cndmask_b32_e32 v0, v0, v3, vcc
	v_mov_b32_e32 v3, s59
	v_cndmask_b32_e32 v1, v1, v3, vcc
	v_add_co_u32_e32 v0, vcc, v0, v194
	s_nop 1
	v_addc_co_u32_e32 v1, vcc, 0, v1, vcc
	global_load_dwordx4 v[120:123], v[0:1], off
	v_add_u32_e32 v194, 0x4000, v194
	v_add_u32_e32 v195, 24, v192
	v_cmp_gt_u32_e32 vcc, 0x1000, v195
	v_mov_b32_e32 v0, s98
	v_mov_b32_e32 v1, s99
	v_mov_b32_e32 v3, s58
	v_cndmask_b32_e32 v0, v0, v3, vcc
	v_mov_b32_e32 v3, s59
	v_cndmask_b32_e32 v1, v1, v3, vcc
	v_add_co_u32_e32 v0, vcc, v0, v194
	s_nop 1
	v_addc_co_u32_e32 v1, vcc, 0, v1, vcc
	global_load_dwordx4 v[124:127], v[0:1], off
	v_add_u32_e32 v194, 0x4000, v194
	v_add_u32_e32 v195, 28, v192
	v_cmp_gt_u32_e32 vcc, 0x1000, v195
	v_mov_b32_e32 v0, s98
	v_mov_b32_e32 v1, s99
	v_mov_b32_e32 v3, s58
	v_cndmask_b32_e32 v0, v0, v3, vcc
	v_mov_b32_e32 v3, s59
	v_cndmask_b32_e32 v1, v1, v3, vcc
	v_add_co_u32_e32 v0, vcc, v0, v194
	s_nop 1
	v_addc_co_u32_e32 v1, vcc, 0, v1, vcc
	global_load_dwordx4 v[128:131], v[0:1], off
	v_add_u32_e32 v194, 0x4000, v194
	v_add_u32_e32 v195, 32, v192
	v_cmp_gt_u32_e32 vcc, 0x1000, v195
	v_mov_b32_e32 v0, s98
	v_mov_b32_e32 v1, s99
	v_mov_b32_e32 v3, s58
	v_cndmask_b32_e32 v0, v0, v3, vcc
	v_mov_b32_e32 v3, s59
	v_cndmask_b32_e32 v1, v1, v3, vcc
	v_add_co_u32_e32 v0, vcc, v0, v194
	s_nop 1
	v_addc_co_u32_e32 v1, vcc, 0, v1, vcc
	global_load_dwordx4 v[132:135], v[0:1], off
	v_add_u32_e32 v194, 0x4000, v194
	v_add_u32_e32 v195, 36, v192
	v_cmp_gt_u32_e32 vcc, 0x1000, v195
	v_mov_b32_e32 v0, s98
	v_mov_b32_e32 v1, s99
	v_mov_b32_e32 v3, s58
	v_cndmask_b32_e32 v0, v0, v3, vcc
	v_mov_b32_e32 v3, s59
	v_cndmask_b32_e32 v1, v1, v3, vcc
	v_add_co_u32_e32 v0, vcc, v0, v194
	s_nop 1
	v_addc_co_u32_e32 v1, vcc, 0, v1, vcc
	global_load_dwordx4 v[136:139], v[0:1], off
	v_add_u32_e32 v194, 0x4000, v194
	v_add_u32_e32 v195, 40, v192
	v_cmp_gt_u32_e32 vcc, 0x1000, v195
	v_mov_b32_e32 v0, s98
	v_mov_b32_e32 v1, s99
	v_mov_b32_e32 v3, s58
	v_cndmask_b32_e32 v0, v0, v3, vcc
	v_mov_b32_e32 v3, s59
	v_cndmask_b32_e32 v1, v1, v3, vcc
	v_add_co_u32_e32 v0, vcc, v0, v194
	s_nop 1
	v_addc_co_u32_e32 v1, vcc, 0, v1, vcc
	global_load_dwordx4 v[140:143], v[0:1], off
	v_add_u32_e32 v194, 0x4000, v194
	v_add_u32_e32 v195, 44, v192
	v_cmp_gt_u32_e32 vcc, 0x1000, v195
	v_mov_b32_e32 v0, s98
	v_mov_b32_e32 v1, s99
	v_mov_b32_e32 v3, s58
	v_cndmask_b32_e32 v0, v0, v3, vcc
	v_mov_b32_e32 v3, s59
	v_cndmask_b32_e32 v1, v1, v3, vcc
	v_add_co_u32_e32 v0, vcc, v0, v194
	s_nop 1
	v_addc_co_u32_e32 v1, vcc, 0, v1, vcc
	global_load_dwordx4 v[144:147], v[0:1], off
	v_add_u32_e32 v194, 0x4000, v194
	v_add_u32_e32 v195, s4, v193
	global_load_dwordx4 v[148:151], v195, s[100:101]
	v_add_u32_e32 v195, s5, v193
	global_load_dwordx4 v[152:155], v195, s[100:101]
	ds_write_b32 v203, v4 offset:0
	ds_write_b32 v203, v5 offset:272
	ds_write_b32 v203, v6 offset:544
	ds_write_b32 v203, v7 offset:816
	ds_write_b32 v203, v8 offset:64
	ds_write_b32 v203, v9 offset:336
	ds_write_b32 v203, v10 offset:608
	ds_write_b32 v203, v11 offset:880
	ds_write_b32 v203, v12 offset:128
	ds_write_b32 v203, v13 offset:400
	ds_write_b32 v203, v14 offset:672
	ds_write_b32 v203, v15 offset:944
	ds_write_b32 v203, v16 offset:192
	ds_write_b32 v203, v17 offset:464
	ds_write_b32 v203, v18 offset:736
	ds_write_b32 v203, v19 offset:1008
	s_waitcnt lgkmcnt(0)
	ds_read_b128 v[156:159], v204 offset:0
	ds_read_b128 v[160:163], v204 offset:1088
	ds_read_b128 v[164:167], v204 offset:2176
	ds_read_b128 v[168:171], v204 offset:3264
	s_waitcnt lgkmcnt(0)
	v_add_u32_e32 v195, 48, v192
	v_cmp_gt_u32_e32 vcc, 0x1000, v195
	v_mov_b32_e32 v0, s98
	v_mov_b32_e32 v1, s99
	v_mov_b32_e32 v3, s58
	v_cndmask_b32_e32 v0, v0, v3, vcc
	v_mov_b32_e32 v3, s59
	v_cndmask_b32_e32 v1, v1, v3, vcc
	v_add_co_u32_e32 v0, vcc, v0, v194
	s_nop 1
	v_addc_co_u32_e32 v1, vcc, 0, v1, vcc
	global_load_dwordx4 v[4:7], v[0:1], off
	v_add_u32_e32 v194, 0x4000, v194
	v_add_u32_e32 v195, 52, v192
	v_cmp_gt_u32_e32 vcc, 0x1000, v195
	v_mov_b32_e32 v0, s98
	v_mov_b32_e32 v1, s99
	v_mov_b32_e32 v3, s58
	v_cndmask_b32_e32 v0, v0, v3, vcc
	v_mov_b32_e32 v3, s59
	v_cndmask_b32_e32 v1, v1, v3, vcc
	v_add_co_u32_e32 v0, vcc, v0, v194
	s_nop 1
	v_addc_co_u32_e32 v1, vcc, 0, v1, vcc
	global_load_dwordx4 v[8:11], v[0:1], off
	v_add_u32_e32 v194, 0x4000, v194
	v_add_u32_e32 v195, 56, v192
	v_cmp_gt_u32_e32 vcc, 0x1000, v195
	v_mov_b32_e32 v0, s98
	v_mov_b32_e32 v1, s99
	v_mov_b32_e32 v3, s58
	v_cndmask_b32_e32 v0, v0, v3, vcc
	v_mov_b32_e32 v3, s59
	v_cndmask_b32_e32 v1, v1, v3, vcc
	v_add_co_u32_e32 v0, vcc, v0, v194
	s_nop 1
	v_addc_co_u32_e32 v1, vcc, 0, v1, vcc
	global_load_dwordx4 v[12:15], v[0:1], off
	v_add_u32_e32 v194, 0x4000, v194
	v_add_u32_e32 v195, 60, v192
	v_cmp_gt_u32_e32 vcc, 0x1000, v195
	v_mov_b32_e32 v0, s98
	v_mov_b32_e32 v1, s99
	v_mov_b32_e32 v3, s58
	v_cndmask_b32_e32 v0, v0, v3, vcc
	v_mov_b32_e32 v3, s59
	v_cndmask_b32_e32 v1, v1, v3, vcc
	v_add_co_u32_e32 v0, vcc, v0, v194
	s_nop 1
	v_addc_co_u32_e32 v1, vcc, 0, v1, vcc
	global_load_dwordx4 v[16:19], v[0:1], off
	v_add_u32_e32 v194, 0x4000, v194
	v_add_u32_e32 v195, 0, v192
	v_cmp_le_u32_e32 vcc, s7, v195
	s_waitcnt vmcnt(4)
	v_cndmask_b32_e32 v172, v148, v152, vcc
	v_cndmask_b32_e32 v173, v149, v153, vcc
	v_cndmask_b32_e32 v174, v150, v154, vcc
	v_cndmask_b32_e32 v175, v151, v155, vcc
	v_fmac_f32_e32 v100, v172, v156
	v_fmac_f32_e32 v101, v173, v157
	v_fmac_f32_e32 v102, v174, v158
	v_fmac_f32_e32 v103, v175, v159
	global_store_dwordx4 v197, v[100:103], s[56:57] sc0 sc1
	v_add_u32_e32 v197, 0x4000, v197
	v_add_u32_e32 v195, 4, v192
	v_cmp_le_u32_e32 vcc, s7, v195
	s_waitcnt vmcnt(5)
	s_waitcnt lgkmcnt(2)
	v_cndmask_b32_e32 v172, v148, v152, vcc
	v_cndmask_b32_e32 v173, v149, v153, vcc
	v_cndmask_b32_e32 v174, v150, v154, vcc
	v_cndmask_b32_e32 v175, v151, v155, vcc
	v_fmac_f32_e32 v104, v172, v160
	v_fmac_f32_e32 v105, v173, v161
	v_fmac_f32_e32 v106, v174, v162
	v_fmac_f32_e32 v107, v175, v163
	global_store_dwordx4 v197, v[104:107], s[56:57] sc0 sc1
	v_add_u32_e32 v197, 0x4000, v197
	v_add_u32_e32 v195, 8, v192
	v_cmp_le_u32_e32 vcc, s7, v195
	s_waitcnt vmcnt(6)
	s_waitcnt lgkmcnt(1)
	v_cndmask_b32_e32 v172, v148, v152, vcc
	v_cndmask_b32_e32 v173, v149, v153, vcc
	v_cndmask_b32_e32 v174, v150, v154, vcc
	v_cndmask_b32_e32 v175, v151, v155, vcc
	v_fmac_f32_e32 v108, v172, v164
	v_fmac_f32_e32 v109, v173, v165
	v_fmac_f32_e32 v110, v174, v166
	v_fmac_f32_e32 v111, v175, v167
	global_store_dwordx4 v197, v[108:111], s[56:57] sc0 sc1
	v_add_u32_e32 v197, 0x4000, v197
	v_add_u32_e32 v195, 12, v192
	v_cmp_le_u32_e32 vcc, s7, v195
	s_waitcnt vmcnt(7)
	s_waitcnt lgkmcnt(0)
	v_cndmask_b32_e32 v172, v148, v152, vcc
	v_cndmask_b32_e32 v173, v149, v153, vcc
	v_cndmask_b32_e32 v174, v150, v154, vcc
	v_cndmask_b32_e32 v175, v151, v155, vcc
	v_fmac_f32_e32 v112, v172, v168
	v_fmac_f32_e32 v113, v173, v169
	v_fmac_f32_e32 v114, v174, v170
	v_fmac_f32_e32 v115, v175, v171
	global_store_dwordx4 v197, v[112:115], s[56:57] sc0 sc1
	v_add_u32_e32 v197, 0x4000, v197
	ds_write_b32 v203, v20 offset:0
	ds_write_b32 v203, v21 offset:272
	ds_write_b32 v203, v22 offset:544
	ds_write_b32 v203, v23 offset:816
	ds_write_b32 v203, v24 offset:64
	ds_write_b32 v203, v25 offset:336
	ds_write_b32 v203, v26 offset:608
	ds_write_b32 v203, v27 offset:880
	ds_write_b32 v203, v28 offset:128
	ds_write_b32 v203, v29 offset:400
	ds_write_b32 v203, v30 offset:672
	ds_write_b32 v203, v31 offset:944
	ds_write_b32 v203, v32 offset:192
	ds_write_b32 v203, v33 offset:464
	ds_write_b32 v203, v34 offset:736
	ds_write_b32 v203, v35 offset:1008
	s_waitcnt lgkmcnt(0)
	ds_read_b128 v[156:159], v204 offset:0
	ds_read_b128 v[160:163], v204 offset:1088
	ds_read_b128 v[164:167], v204 offset:2176
	ds_read_b128 v[168:171], v204 offset:3264
	s_waitcnt lgkmcnt(0)
	v_add_u32_e32 v195, 64, v192
	v_cmp_gt_u32_e32 vcc, 0x1000, v195
	v_mov_b32_e32 v0, s98
	v_mov_b32_e32 v1, s99
	v_mov_b32_e32 v3, s58
	v_cndmask_b32_e32 v0, v0, v3, vcc
	v_mov_b32_e32 v3, s59
	v_cndmask_b32_e32 v1, v1, v3, vcc
	v_add_co_u32_e32 v0, vcc, v0, v194
	s_nop 1
	v_addc_co_u32_e32 v1, vcc, 0, v1, vcc
	global_load_dwordx4 v[20:23], v[0:1], off
	v_add_u32_e32 v194, 0x4000, v194
	v_add_u32_e32 v195, 68, v192
	v_cmp_gt_u32_e32 vcc, 0x1000, v195
	v_mov_b32_e32 v0, s98
	v_mov_b32_e32 v1, s99
	v_mov_b32_e32 v3, s58
	v_cndmask_b32_e32 v0, v0, v3, vcc
	v_mov_b32_e32 v3, s59
	v_cndmask_b32_e32 v1, v1, v3, vcc
	v_add_co_u32_e32 v0, vcc, v0, v194
	s_nop 1
	v_addc_co_u32_e32 v1, vcc, 0, v1, vcc
	global_load_dwordx4 v[24:27], v[0:1], off
	v_add_u32_e32 v194, 0x4000, v194
	v_add_u32_e32 v195, 72, v192
	v_cmp_gt_u32_e32 vcc, 0x1000, v195
	v_mov_b32_e32 v0, s98
	v_mov_b32_e32 v1, s99
	v_mov_b32_e32 v3, s58
	v_cndmask_b32_e32 v0, v0, v3, vcc
	v_mov_b32_e32 v3, s59
	v_cndmask_b32_e32 v1, v1, v3, vcc
	v_add_co_u32_e32 v0, vcc, v0, v194
	s_nop 1
	v_addc_co_u32_e32 v1, vcc, 0, v1, vcc
	global_load_dwordx4 v[28:31], v[0:1], off
	v_add_u32_e32 v194, 0x4000, v194
	v_add_u32_e32 v195, 76, v192
	v_cmp_gt_u32_e32 vcc, 0x1000, v195
	v_mov_b32_e32 v0, s98
	v_mov_b32_e32 v1, s99
	v_mov_b32_e32 v3, s58
	v_cndmask_b32_e32 v0, v0, v3, vcc
	v_mov_b32_e32 v3, s59
	v_cndmask_b32_e32 v1, v1, v3, vcc
	v_add_co_u32_e32 v0, vcc, v0, v194
	s_nop 1
	v_addc_co_u32_e32 v1, vcc, 0, v1, vcc
	global_load_dwordx4 v[32:35], v[0:1], off
	v_add_u32_e32 v194, 0x4000, v194
	v_add_u32_e32 v195, 16, v192
	v_cmp_le_u32_e32 vcc, s7, v195
	s_waitcnt vmcnt(12)
	v_cndmask_b32_e32 v172, v148, v152, vcc
	v_cndmask_b32_e32 v173, v149, v153, vcc
	v_cndmask_b32_e32 v174, v150, v154, vcc
	v_cndmask_b32_e32 v175, v151, v155, vcc
	v_fmac_f32_e32 v116, v172, v156
	v_fmac_f32_e32 v117, v173, v157
	v_fmac_f32_e32 v118, v174, v158
	v_fmac_f32_e32 v119, v175, v159
	global_store_dwordx4 v197, v[116:119], s[56:57] sc0 sc1
	v_add_u32_e32 v197, 0x4000, v197
	v_add_u32_e32 v195, 20, v192
	v_cmp_le_u32_e32 vcc, s7, v195
	s_waitcnt vmcnt(13)
	s_waitcnt lgkmcnt(2)
	v_cndmask_b32_e32 v172, v148, v152, vcc
	v_cndmask_b32_e32 v173, v149, v153, vcc
	v_cndmask_b32_e32 v174, v150, v154, vcc
	v_cndmask_b32_e32 v175, v151, v155, vcc
	v_fmac_f32_e32 v120, v172, v160
	v_fmac_f32_e32 v121, v173, v161
	v_fmac_f32_e32 v122, v174, v162
	v_fmac_f32_e32 v123, v175, v163
	global_store_dwordx4 v197, v[120:123], s[56:57] sc0 sc1
	v_add_u32_e32 v197, 0x4000, v197
	v_add_u32_e32 v195, 24, v192
	v_cmp_le_u32_e32 vcc, s7, v195
	s_waitcnt vmcnt(14)
	s_waitcnt lgkmcnt(1)
	v_cndmask_b32_e32 v172, v148, v152, vcc
	v_cndmask_b32_e32 v173, v149, v153, vcc
	v_cndmask_b32_e32 v174, v150, v154, vcc
	v_cndmask_b32_e32 v175, v151, v155, vcc
	v_fmac_f32_e32 v124, v172, v164
	v_fmac_f32_e32 v125, v173, v165
	v_fmac_f32_e32 v126, v174, v166
	v_fmac_f32_e32 v127, v175, v167
	global_store_dwordx4 v197, v[124:127], s[56:57] sc0 sc1
	v_add_u32_e32 v197, 0x4000, v197
	v_add_u32_e32 v195, 28, v192
	v_cmp_le_u32_e32 vcc, s7, v195
	s_waitcnt vmcnt(15)
	s_waitcnt lgkmcnt(0)
	v_cndmask_b32_e32 v172, v148, v152, vcc
	v_cndmask_b32_e32 v173, v149, v153, vcc
	v_cndmask_b32_e32 v174, v150, v154, vcc
	v_cndmask_b32_e32 v175, v151, v155, vcc
	v_fmac_f32_e32 v128, v172, v168
	v_fmac_f32_e32 v129, v173, v169
	v_fmac_f32_e32 v130, v174, v170
	v_fmac_f32_e32 v131, v175, v171
	global_store_dwordx4 v197, v[128:131], s[56:57] sc0 sc1
	v_add_u32_e32 v197, 0x4000, v197
	ds_write_b32 v203, v36 offset:0
	ds_write_b32 v203, v37 offset:272
	ds_write_b32 v203, v38 offset:544
	ds_write_b32 v203, v39 offset:816
	ds_write_b32 v203, v40 offset:64
	ds_write_b32 v203, v41 offset:336
	ds_write_b32 v203, v42 offset:608
	ds_write_b32 v203, v43 offset:880
	ds_write_b32 v203, v44 offset:128
	ds_write_b32 v203, v45 offset:400
	ds_write_b32 v203, v46 offset:672
	ds_write_b32 v203, v47 offset:944
	ds_write_b32 v203, v48 offset:192
	ds_write_b32 v203, v49 offset:464
	ds_write_b32 v203, v50 offset:736
	ds_write_b32 v203, v51 offset:1008
	s_waitcnt lgkmcnt(0)
	ds_read_b128 v[156:159], v204 offset:0
	ds_read_b128 v[160:163], v204 offset:1088
	ds_read_b128 v[164:167], v204 offset:2176
	ds_read_b128 v[168:171], v204 offset:3264
	s_waitcnt lgkmcnt(0)
	v_add_u32_e32 v195, 80, v192
	v_cmp_gt_u32_e32 vcc, 0x1000, v195
	v_mov_b32_e32 v0, s98
	v_mov_b32_e32 v1, s99
	v_mov_b32_e32 v3, s58
	v_cndmask_b32_e32 v0, v0, v3, vcc
	v_mov_b32_e32 v3, s59
	v_cndmask_b32_e32 v1, v1, v3, vcc
	v_add_co_u32_e32 v0, vcc, v0, v194
	s_nop 1
	v_addc_co_u32_e32 v1, vcc, 0, v1, vcc
	global_load_dwordx4 v[36:39], v[0:1], off
	v_add_u32_e32 v194, 0x4000, v194
	v_add_u32_e32 v195, 84, v192
	v_cmp_gt_u32_e32 vcc, 0x1000, v195
	v_mov_b32_e32 v0, s98
	v_mov_b32_e32 v1, s99
	v_mov_b32_e32 v3, s58
	v_cndmask_b32_e32 v0, v0, v3, vcc
	v_mov_b32_e32 v3, s59
	v_cndmask_b32_e32 v1, v1, v3, vcc
	v_add_co_u32_e32 v0, vcc, v0, v194
	s_nop 1
	v_addc_co_u32_e32 v1, vcc, 0, v1, vcc
	global_load_dwordx4 v[40:43], v[0:1], off
	v_add_u32_e32 v194, 0x4000, v194
	v_add_u32_e32 v195, 88, v192
	v_cmp_gt_u32_e32 vcc, 0x1000, v195
	v_mov_b32_e32 v0, s98
	v_mov_b32_e32 v1, s99
	v_mov_b32_e32 v3, s58
	v_cndmask_b32_e32 v0, v0, v3, vcc
	v_mov_b32_e32 v3, s59
	v_cndmask_b32_e32 v1, v1, v3, vcc
	v_add_co_u32_e32 v0, vcc, v0, v194
	s_nop 1
	v_addc_co_u32_e32 v1, vcc, 0, v1, vcc
	global_load_dwordx4 v[44:47], v[0:1], off
	v_add_u32_e32 v194, 0x4000, v194
	v_add_u32_e32 v195, 92, v192
	v_cmp_gt_u32_e32 vcc, 0x1000, v195
	v_mov_b32_e32 v0, s98
	v_mov_b32_e32 v1, s99
	v_mov_b32_e32 v3, s58
	v_cndmask_b32_e32 v0, v0, v3, vcc
	v_mov_b32_e32 v3, s59
	v_cndmask_b32_e32 v1, v1, v3, vcc
	v_add_co_u32_e32 v0, vcc, v0, v194
	s_nop 1
	v_addc_co_u32_e32 v1, vcc, 0, v1, vcc
	global_load_dwordx4 v[48:51], v[0:1], off
	v_add_u32_e32 v194, 0x4000, v194
	v_add_u32_e32 v195, 32, v192
	v_cmp_le_u32_e32 vcc, s7, v195
	s_waitcnt vmcnt(20)
	v_cndmask_b32_e32 v172, v148, v152, vcc
	v_cndmask_b32_e32 v173, v149, v153, vcc
	v_cndmask_b32_e32 v174, v150, v154, vcc
	v_cndmask_b32_e32 v175, v151, v155, vcc
	v_fmac_f32_e32 v132, v172, v156
	v_fmac_f32_e32 v133, v173, v157
	v_fmac_f32_e32 v134, v174, v158
	v_fmac_f32_e32 v135, v175, v159
	global_store_dwordx4 v197, v[132:135], s[56:57] sc0 sc1
	v_add_u32_e32 v197, 0x4000, v197
	v_add_u32_e32 v195, 36, v192
	v_cmp_le_u32_e32 vcc, s7, v195
	s_waitcnt vmcnt(21)
	s_waitcnt lgkmcnt(2)
	v_cndmask_b32_e32 v172, v148, v152, vcc
	v_cndmask_b32_e32 v173, v149, v153, vcc
	v_cndmask_b32_e32 v174, v150, v154, vcc
	v_cndmask_b32_e32 v175, v151, v155, vcc
	v_fmac_f32_e32 v136, v172, v160
	v_fmac_f32_e32 v137, v173, v161
	v_fmac_f32_e32 v138, v174, v162
	v_fmac_f32_e32 v139, v175, v163
	global_store_dwordx4 v197, v[136:139], s[56:57] sc0 sc1
	v_add_u32_e32 v197, 0x4000, v197
	v_add_u32_e32 v195, 40, v192
	v_cmp_le_u32_e32 vcc, s7, v195
	s_waitcnt vmcnt(22)
	s_waitcnt lgkmcnt(1)
	v_cndmask_b32_e32 v172, v148, v152, vcc
	v_cndmask_b32_e32 v173, v149, v153, vcc
	v_cndmask_b32_e32 v174, v150, v154, vcc
	v_cndmask_b32_e32 v175, v151, v155, vcc
	v_fmac_f32_e32 v140, v172, v164
	v_fmac_f32_e32 v141, v173, v165
	v_fmac_f32_e32 v142, v174, v166
	v_fmac_f32_e32 v143, v175, v167
	global_store_dwordx4 v197, v[140:143], s[56:57] sc0 sc1
	v_add_u32_e32 v197, 0x4000, v197
	v_add_u32_e32 v195, 44, v192
	v_cmp_le_u32_e32 vcc, s7, v195
	s_waitcnt vmcnt(23)
	s_waitcnt lgkmcnt(0)
	v_cndmask_b32_e32 v172, v148, v152, vcc
	v_cndmask_b32_e32 v173, v149, v153, vcc
	v_cndmask_b32_e32 v174, v150, v154, vcc
	v_cndmask_b32_e32 v175, v151, v155, vcc
	v_fmac_f32_e32 v144, v172, v168
	v_fmac_f32_e32 v145, v173, v169
	v_fmac_f32_e32 v146, v174, v170
	v_fmac_f32_e32 v147, v175, v171
	global_store_dwordx4 v197, v[144:147], s[56:57] sc0 sc1
	v_add_u32_e32 v197, 0x4000, v197
	ds_write_b32 v203, v52 offset:0
	ds_write_b32 v203, v53 offset:272
	ds_write_b32 v203, v54 offset:544
	ds_write_b32 v203, v55 offset:816
	ds_write_b32 v203, v56 offset:64
	ds_write_b32 v203, v57 offset:336
	ds_write_b32 v203, v58 offset:608
	ds_write_b32 v203, v59 offset:880
	ds_write_b32 v203, v60 offset:128
	ds_write_b32 v203, v61 offset:400
	ds_write_b32 v203, v62 offset:672
	ds_write_b32 v203, v63 offset:944
	ds_write_b32 v203, v64 offset:192
	ds_write_b32 v203, v65 offset:464
	ds_write_b32 v203, v66 offset:736
	ds_write_b32 v203, v67 offset:1008
	s_waitcnt lgkmcnt(0)
	ds_read_b128 v[156:159], v204 offset:0
	ds_read_b128 v[160:163], v204 offset:1088
	ds_read_b128 v[164:167], v204 offset:2176
	ds_read_b128 v[168:171], v204 offset:3264
	v_add_u32_e32 v195, 48, v192
	v_cmp_le_u32_e32 vcc, s7, v195
	s_waitcnt vmcnt(23)
	s_waitcnt lgkmcnt(3)
	v_cndmask_b32_e32 v172, v148, v152, vcc
	v_cndmask_b32_e32 v173, v149, v153, vcc
	v_cndmask_b32_e32 v174, v150, v154, vcc
	v_cndmask_b32_e32 v175, v151, v155, vcc
	v_fmac_f32_e32 v4, v172, v156
	v_fmac_f32_e32 v5, v173, v157
	v_fmac_f32_e32 v6, v174, v158
	v_fmac_f32_e32 v7, v175, v159
	global_store_dwordx4 v197, v[4:7], s[56:57] sc0 sc1
	v_add_u32_e32 v197, 0x4000, v197
	v_add_u32_e32 v195, 52, v192
	v_cmp_le_u32_e32 vcc, s7, v195
	s_waitcnt vmcnt(23)
	s_waitcnt lgkmcnt(2)
	v_cndmask_b32_e32 v172, v148, v152, vcc
	v_cndmask_b32_e32 v173, v149, v153, vcc
	v_cndmask_b32_e32 v174, v150, v154, vcc
	v_cndmask_b32_e32 v175, v151, v155, vcc
	v_fmac_f32_e32 v8, v172, v160
	v_fmac_f32_e32 v9, v173, v161
	v_fmac_f32_e32 v10, v174, v162
	v_fmac_f32_e32 v11, v175, v163
	global_store_dwordx4 v197, v[8:11], s[56:57] sc0 sc1
	v_add_u32_e32 v197, 0x4000, v197
	v_add_u32_e32 v195, 56, v192
	v_cmp_le_u32_e32 vcc, s7, v195
	s_waitcnt vmcnt(23)
	s_waitcnt lgkmcnt(1)
	v_cndmask_b32_e32 v172, v148, v152, vcc
	v_cndmask_b32_e32 v173, v149, v153, vcc
	v_cndmask_b32_e32 v174, v150, v154, vcc
	v_cndmask_b32_e32 v175, v151, v155, vcc
	v_fmac_f32_e32 v12, v172, v164
	v_fmac_f32_e32 v13, v173, v165
	v_fmac_f32_e32 v14, v174, v166
	v_fmac_f32_e32 v15, v175, v167
	global_store_dwordx4 v197, v[12:15], s[56:57] sc0 sc1
	v_add_u32_e32 v197, 0x4000, v197
	v_add_u32_e32 v195, 60, v192
	v_cmp_le_u32_e32 vcc, s7, v195
	s_waitcnt vmcnt(23)
	s_waitcnt lgkmcnt(0)
	v_cndmask_b32_e32 v172, v148, v152, vcc
	v_cndmask_b32_e32 v173, v149, v153, vcc
	v_cndmask_b32_e32 v174, v150, v154, vcc
	v_cndmask_b32_e32 v175, v151, v155, vcc
	v_fmac_f32_e32 v16, v172, v168
	v_fmac_f32_e32 v17, v173, v169
	v_fmac_f32_e32 v18, v174, v170
	v_fmac_f32_e32 v19, v175, v171
	global_store_dwordx4 v197, v[16:19], s[56:57] sc0 sc1
	v_add_u32_e32 v197, 0x4000, v197
	ds_write_b32 v203, v68 offset:0
	ds_write_b32 v203, v69 offset:272
	ds_write_b32 v203, v70 offset:544
	ds_write_b32 v203, v71 offset:816
	ds_write_b32 v203, v72 offset:64
	ds_write_b32 v203, v73 offset:336
	ds_write_b32 v203, v74 offset:608
	ds_write_b32 v203, v75 offset:880
	ds_write_b32 v203, v76 offset:128
	ds_write_b32 v203, v77 offset:400
	ds_write_b32 v203, v78 offset:672
	ds_write_b32 v203, v79 offset:944
	ds_write_b32 v203, v80 offset:192
	ds_write_b32 v203, v81 offset:464
	ds_write_b32 v203, v82 offset:736
	ds_write_b32 v203, v83 offset:1008
	s_waitcnt lgkmcnt(0)
	ds_read_b128 v[156:159], v204 offset:0
	ds_read_b128 v[160:163], v204 offset:1088
	ds_read_b128 v[164:167], v204 offset:2176
	ds_read_b128 v[168:171], v204 offset:3264
	v_add_u32_e32 v195, 64, v192
	v_cmp_le_u32_e32 vcc, s7, v195
	s_waitcnt vmcnt(19)
	s_waitcnt lgkmcnt(3)
	v_cndmask_b32_e32 v172, v148, v152, vcc
	v_cndmask_b32_e32 v173, v149, v153, vcc
	v_cndmask_b32_e32 v174, v150, v154, vcc
	v_cndmask_b32_e32 v175, v151, v155, vcc
	v_fmac_f32_e32 v20, v172, v156
	v_fmac_f32_e32 v21, v173, v157
	v_fmac_f32_e32 v22, v174, v158
	v_fmac_f32_e32 v23, v175, v159
	global_store_dwordx4 v197, v[20:23], s[56:57] sc0 sc1
	v_add_u32_e32 v197, 0x4000, v197
	v_add_u32_e32 v195, 68, v192
	v_cmp_le_u32_e32 vcc, s7, v195
	s_waitcnt vmcnt(19)
	s_waitcnt lgkmcnt(2)
	v_cndmask_b32_e32 v172, v148, v152, vcc
	v_cndmask_b32_e32 v173, v149, v153, vcc
	v_cndmask_b32_e32 v174, v150, v154, vcc
	v_cndmask_b32_e32 v175, v151, v155, vcc
	v_fmac_f32_e32 v24, v172, v160
	v_fmac_f32_e32 v25, v173, v161
	v_fmac_f32_e32 v26, v174, v162
	v_fmac_f32_e32 v27, v175, v163
	global_store_dwordx4 v197, v[24:27], s[56:57] sc0 sc1
	v_add_u32_e32 v197, 0x4000, v197
	v_add_u32_e32 v195, 72, v192
	v_cmp_le_u32_e32 vcc, s7, v195
	s_waitcnt vmcnt(19)
	s_waitcnt lgkmcnt(1)
	v_cndmask_b32_e32 v172, v148, v152, vcc
	v_cndmask_b32_e32 v173, v149, v153, vcc
	v_cndmask_b32_e32 v174, v150, v154, vcc
	v_cndmask_b32_e32 v175, v151, v155, vcc
	v_fmac_f32_e32 v28, v172, v164
	v_fmac_f32_e32 v29, v173, v165
	v_fmac_f32_e32 v30, v174, v166
	v_fmac_f32_e32 v31, v175, v167
	global_store_dwordx4 v197, v[28:31], s[56:57] sc0 sc1
	v_add_u32_e32 v197, 0x4000, v197
	v_add_u32_e32 v195, 76, v192
	v_cmp_le_u32_e32 vcc, s7, v195
	s_waitcnt vmcnt(19)
	s_waitcnt lgkmcnt(0)
	v_cndmask_b32_e32 v172, v148, v152, vcc
	v_cndmask_b32_e32 v173, v149, v153, vcc
	v_cndmask_b32_e32 v174, v150, v154, vcc
	v_cndmask_b32_e32 v175, v151, v155, vcc
	v_fmac_f32_e32 v32, v172, v168
	v_fmac_f32_e32 v33, v173, v169
	v_fmac_f32_e32 v34, v174, v170
	v_fmac_f32_e32 v35, v175, v171
	global_store_dwordx4 v197, v[32:35], s[56:57] sc0 sc1
	v_add_u32_e32 v197, 0x4000, v197
	ds_write_b32 v203, v84 offset:0
	ds_write_b32 v203, v85 offset:272
	ds_write_b32 v203, v86 offset:544
	ds_write_b32 v203, v87 offset:816
	ds_write_b32 v203, v88 offset:64
	ds_write_b32 v203, v89 offset:336
	ds_write_b32 v203, v90 offset:608
	ds_write_b32 v203, v91 offset:880
	ds_write_b32 v203, v92 offset:128
	ds_write_b32 v203, v93 offset:400
	ds_write_b32 v203, v94 offset:672
	ds_write_b32 v203, v95 offset:944
	ds_write_b32 v203, v96 offset:192
	ds_write_b32 v203, v97 offset:464
	ds_write_b32 v203, v98 offset:736
	ds_write_b32 v203, v99 offset:1008
	s_waitcnt lgkmcnt(0)
	ds_read_b128 v[156:159], v204 offset:0
	ds_read_b128 v[160:163], v204 offset:1088
	ds_read_b128 v[164:167], v204 offset:2176
	ds_read_b128 v[168:171], v204 offset:3264
	v_add_u32_e32 v195, 80, v192
	v_cmp_le_u32_e32 vcc, s7, v195
	s_waitcnt vmcnt(15)
	s_waitcnt lgkmcnt(3)
	v_cndmask_b32_e32 v172, v148, v152, vcc
	v_cndmask_b32_e32 v173, v149, v153, vcc
	v_cndmask_b32_e32 v174, v150, v154, vcc
	v_cndmask_b32_e32 v175, v151, v155, vcc
	v_fmac_f32_e32 v36, v172, v156
	v_fmac_f32_e32 v37, v173, v157
	v_fmac_f32_e32 v38, v174, v158
	v_fmac_f32_e32 v39, v175, v159
	global_store_dwordx4 v197, v[36:39], s[56:57] sc0 sc1
	v_add_u32_e32 v197, 0x4000, v197
	v_add_u32_e32 v195, 84, v192
	v_cmp_le_u32_e32 vcc, s7, v195
	s_waitcnt vmcnt(15)
	s_waitcnt lgkmcnt(2)
	v_cndmask_b32_e32 v172, v148, v152, vcc
	v_cndmask_b32_e32 v173, v149, v153, vcc
	v_cndmask_b32_e32 v174, v150, v154, vcc
	v_cndmask_b32_e32 v175, v151, v155, vcc
	v_fmac_f32_e32 v40, v172, v160
	v_fmac_f32_e32 v41, v173, v161
	v_fmac_f32_e32 v42, v174, v162
	v_fmac_f32_e32 v43, v175, v163
	global_store_dwordx4 v197, v[40:43], s[56:57] sc0 sc1
	v_add_u32_e32 v197, 0x4000, v197
	v_add_u32_e32 v195, 88, v192
	v_cmp_le_u32_e32 vcc, s7, v195
	s_waitcnt vmcnt(15)
	s_waitcnt lgkmcnt(1)
	v_cndmask_b32_e32 v172, v148, v152, vcc
	v_cndmask_b32_e32 v173, v149, v153, vcc
	v_cndmask_b32_e32 v174, v150, v154, vcc
	v_cndmask_b32_e32 v175, v151, v155, vcc
	v_fmac_f32_e32 v44, v172, v164
	v_fmac_f32_e32 v45, v173, v165
	v_fmac_f32_e32 v46, v174, v166
	v_fmac_f32_e32 v47, v175, v167
	global_store_dwordx4 v197, v[44:47], s[56:57] sc0 sc1
	v_add_u32_e32 v197, 0x4000, v197
	v_add_u32_e32 v195, 92, v192
	v_cmp_le_u32_e32 vcc, s7, v195
	s_waitcnt vmcnt(15)
	s_waitcnt lgkmcnt(0)
	v_cndmask_b32_e32 v172, v148, v152, vcc
	v_cndmask_b32_e32 v173, v149, v153, vcc
	v_cndmask_b32_e32 v174, v150, v154, vcc
	v_cndmask_b32_e32 v175, v151, v155, vcc
	v_fmac_f32_e32 v48, v172, v168
	v_fmac_f32_e32 v49, v173, v169
	v_fmac_f32_e32 v50, v174, v170
	v_fmac_f32_e32 v51, v175, v171
	global_store_dwordx4 v197, v[48:51], s[56:57] sc0 sc1
	v_add_u32_e32 v197, 0x4000, v197
	v_mov_b32_e32 v4, 0
	v_mov_b32_e32 v5, 0
	v_mov_b32_e32 v6, 0
	v_mov_b32_e32 v7, 0
	v_mov_b32_e32 v8, 0
	v_mov_b32_e32 v9, 0
	v_mov_b32_e32 v10, 0
	v_mov_b32_e32 v11, 0
	v_mov_b32_e32 v12, 0
	v_mov_b32_e32 v13, 0
	v_mov_b32_e32 v14, 0
	v_mov_b32_e32 v15, 0
	v_mov_b32_e32 v16, 0
	v_mov_b32_e32 v17, 0
	v_mov_b32_e32 v18, 0
	v_mov_b32_e32 v19, 0
	v_mov_b32_e32 v20, 0
	v_mov_b32_e32 v21, 0
	v_mov_b32_e32 v22, 0
	v_mov_b32_e32 v23, 0
	v_mov_b32_e32 v24, 0
	v_mov_b32_e32 v25, 0
	v_mov_b32_e32 v26, 0
	v_mov_b32_e32 v27, 0
	v_mov_b32_e32 v28, 0
	v_mov_b32_e32 v29, 0
	v_mov_b32_e32 v30, 0
	v_mov_b32_e32 v31, 0
	v_mov_b32_e32 v32, 0
	v_mov_b32_e32 v33, 0
	v_mov_b32_e32 v34, 0
	v_mov_b32_e32 v35, 0
	v_mov_b32_e32 v36, 0
	v_mov_b32_e32 v37, 0
	v_mov_b32_e32 v38, 0
	v_mov_b32_e32 v39, 0
	v_mov_b32_e32 v40, 0
	v_mov_b32_e32 v41, 0
	v_mov_b32_e32 v42, 0
	v_mov_b32_e32 v43, 0
	v_mov_b32_e32 v44, 0
	v_mov_b32_e32 v45, 0
	v_mov_b32_e32 v46, 0
	v_mov_b32_e32 v47, 0
	v_mov_b32_e32 v48, 0
	v_mov_b32_e32 v49, 0
	v_mov_b32_e32 v50, 0
	v_mov_b32_e32 v51, 0
	v_mov_b32_e32 v52, 0
	v_mov_b32_e32 v53, 0
	v_mov_b32_e32 v54, 0
	v_mov_b32_e32 v55, 0
	v_mov_b32_e32 v56, 0
	v_mov_b32_e32 v57, 0
	v_mov_b32_e32 v58, 0
	v_mov_b32_e32 v59, 0
	v_mov_b32_e32 v60, 0
	v_mov_b32_e32 v61, 0
	v_mov_b32_e32 v62, 0
	v_mov_b32_e32 v63, 0
	v_mov_b32_e32 v64, 0
	v_mov_b32_e32 v65, 0
	v_mov_b32_e32 v66, 0
	v_mov_b32_e32 v67, 0
	v_mov_b32_e32 v68, 0
	v_mov_b32_e32 v69, 0
	v_mov_b32_e32 v70, 0
	v_mov_b32_e32 v71, 0
	v_mov_b32_e32 v72, 0
	v_mov_b32_e32 v73, 0
	v_mov_b32_e32 v74, 0
	v_mov_b32_e32 v75, 0
	v_mov_b32_e32 v76, 0
	v_mov_b32_e32 v77, 0
	v_mov_b32_e32 v78, 0
	v_mov_b32_e32 v79, 0
	v_mov_b32_e32 v80, 0
	v_mov_b32_e32 v81, 0
	v_mov_b32_e32 v82, 0
	v_mov_b32_e32 v83, 0
	v_mov_b32_e32 v84, 0
	v_mov_b32_e32 v85, 0
	v_mov_b32_e32 v86, 0
	v_mov_b32_e32 v87, 0
	v_mov_b32_e32 v88, 0
	v_mov_b32_e32 v89, 0
	v_mov_b32_e32 v90, 0
	v_mov_b32_e32 v91, 0
	v_mov_b32_e32 v92, 0
	v_mov_b32_e32 v93, 0
	v_mov_b32_e32 v94, 0
	v_mov_b32_e32 v95, 0
	v_mov_b32_e32 v96, 0
	v_mov_b32_e32 v97, 0
	v_mov_b32_e32 v98, 0
	v_mov_b32_e32 v99, 0
	s_mov_b32 s34, 0
	s_add_u32 s35, s35, s52
	s_cmp_ge_u32 s31, s30
	s_cbranch_scc1 .Lgm_f2_exit

.Lgm_wo_join:
	s_waitcnt lgkmcnt(13)
	v_mfma_f32_16x16x32_bf16 v[4:7], v[100:103], v[124:127], v[4:7]
	v_mfma_f32_16x16x32_bf16 v[20:23], v[104:107], v[124:127], v[20:23]
	v_mfma_f32_16x16x32_bf16 v[36:39], v[108:111], v[124:127], v[36:39]
	v_mfma_f32_16x16x32_bf16 v[52:55], v[112:115], v[124:127], v[52:55]
	v_mfma_f32_16x16x32_bf16 v[68:71], v[116:119], v[124:127], v[68:71]
	v_mfma_f32_16x16x32_bf16 v[84:87], v[120:123], v[124:127], v[84:87]
	s_waitcnt lgkmcnt(12)
	v_mfma_f32_16x16x32_bf16 v[8:11], v[100:103], v[128:131], v[8:11]
	v_mfma_f32_16x16x32_bf16 v[24:27], v[104:107], v[128:131], v[24:27]
	v_mfma_f32_16x16x32_bf16 v[40:43], v[108:111], v[128:131], v[40:43]
	v_mfma_f32_16x16x32_bf16 v[56:59], v[112:115], v[128:131], v[56:59]
	v_mfma_f32_16x16x32_bf16 v[72:75], v[116:119], v[128:131], v[72:75]
	v_mfma_f32_16x16x32_bf16 v[88:91], v[120:123], v[128:131], v[88:91]
	s_waitcnt lgkmcnt(11)
	v_mfma_f32_16x16x32_bf16 v[12:15], v[100:103], v[132:135], v[12:15]
	v_mfma_f32_16x16x32_bf16 v[28:31], v[104:107], v[132:135], v[28:31]
	v_mfma_f32_16x16x32_bf16 v[44:47], v[108:111], v[132:135], v[44:47]
	v_mfma_f32_16x16x32_bf16 v[60:63], v[112:115], v[132:135], v[60:63]
	v_mfma_f32_16x16x32_bf16 v[76:79], v[116:119], v[132:135], v[76:79]
	v_mfma_f32_16x16x32_bf16 v[92:95], v[120:123], v[132:135], v[92:95]
	s_waitcnt lgkmcnt(10)
	v_mfma_f32_16x16x32_bf16 v[16:19], v[100:103], v[136:139], v[16:19]
	v_mfma_f32_16x16x32_bf16 v[32:35], v[104:107], v[136:139], v[32:35]
	v_mfma_f32_16x16x32_bf16 v[48:51], v[108:111], v[136:139], v[48:51]
	v_mfma_f32_16x16x32_bf16 v[64:67], v[112:115], v[136:139], v[64:67]
	v_mfma_f32_16x16x32_bf16 v[80:83], v[116:119], v[136:139], v[80:83]
	v_mfma_f32_16x16x32_bf16 v[96:99], v[120:123], v[136:139], v[96:99]
	s_waitcnt lgkmcnt(0)
	s_add_u32 s34, s34, 1
	s_add_u32 s31, s31, 1
	s_cmp_lt_u32 s34, 16
	s_cbranch_scc1 .Lgm_wo_rot
	v_mfma_f32_16x16x32_bf16 v[4:7], v[140:143], v[164:167], v[4:7]
	v_mfma_f32_16x16x32_bf16 v[20:23], v[144:147], v[164:167], v[20:23]
	v_mfma_f32_16x16x32_bf16 v[36:39], v[148:151], v[164:167], v[36:39]
	v_mfma_f32_16x16x32_bf16 v[52:55], v[152:155], v[164:167], v[52:55]
	v_mfma_f32_16x16x32_bf16 v[68:71], v[156:159], v[164:167], v[68:71]
	v_mfma_f32_16x16x32_bf16 v[84:87], v[160:163], v[164:167], v[84:87]
	v_mfma_f32_16x16x32_bf16 v[8:11], v[140:143], v[168:171], v[8:11]
	v_mfma_f32_16x16x32_bf16 v[24:27], v[144:147], v[168:171], v[24:27]
	v_mfma_f32_16x16x32_bf16 v[40:43], v[148:151], v[168:171], v[40:43]
	v_mfma_f32_16x16x32_bf16 v[56:59], v[152:155], v[168:171], v[56:59]
	v_mfma_f32_16x16x32_bf16 v[72:75], v[156:159], v[168:171], v[72:75]
	v_mfma_f32_16x16x32_bf16 v[88:91], v[160:163], v[168:171], v[88:91]
	v_mfma_f32_16x16x32_bf16 v[12:15], v[140:143], v[172:175], v[12:15]
	v_mfma_f32_16x16x32_bf16 v[28:31], v[144:147], v[172:175], v[28:31]
	v_mfma_f32_16x16x32_bf16 v[44:47], v[148:151], v[172:175], v[44:47]
	v_mfma_f32_16x16x32_bf16 v[60:63], v[152:155], v[172:175], v[60:63]
	v_mfma_f32_16x16x32_bf16 v[76:79], v[156:159], v[172:175], v[76:79]
	v_mfma_f32_16x16x32_bf16 v[92:95], v[160:163], v[172:175], v[92:95]
	v_mfma_f32_16x16x32_bf16 v[16:19], v[140:143], v[176:179], v[16:19]
	v_mfma_f32_16x16x32_bf16 v[32:35], v[144:147], v[176:179], v[32:35]
	v_mfma_f32_16x16x32_bf16 v[48:51], v[148:151], v[176:179], v[48:51]
	v_mfma_f32_16x16x32_bf16 v[64:67], v[152:155], v[176:179], v[64:67]
	v_mfma_f32_16x16x32_bf16 v[80:83], v[156:159], v[176:179], v[80:83]
	v_mfma_f32_16x16x32_bf16 v[96:99], v[160:163], v[176:179], v[96:99]
	s_and_b32 s6, s35, 31
	s_mul_i32 s6, s6, 192
	s_lshr_b32 s7, s35, 5
	s_lshl_b32 s7, s7, 7
	s_nop 7
	s_mul_i32 s4, s6, 0x1000
	s_lshl_b32 s5, s7, 2
	s_add_u32 s4, s4, s5
	v_add_u32_e32 v197, s4, v205
	v_add_u32_e32 v192, s6, v190
	v_lshl_add_u32 v193, s7, 2, v191
	s_sub_i32 s4, s6, 0xc00
	s_max_i32 s4, s4, 0
	s_lshr_b32 s4, s4, 10
	s_add_i32 s5, s6, -2881
	s_max_i32 s5, s5, 0
	s_lshr_b32 s5, s5, 10
	s_movk_i32 s7, 0x1400
	s_cmp_eq_u32 s4, 0
	s_cselect_b32 s7, 0x1000, s7
	s_mul_i32 s4, s4, 0x6000
	s_mul_i32 s5, s5, 0x6000
	v_mov_b32_e32 v194, v197
	v_add_u32_e32 v195, 0, v192
	v_cmp_gt_u32_e32 vcc, 0x1000, v195
	v_mov_b32_e32 v0, s98
	v_mov_b32_e32 v1, s99
	v_mov_b32_e32 v3, s58
	v_cndmask_b32_e32 v0, v0, v3, vcc
	v_mov_b32_e32 v3, s59
	v_cndmask_b32_e32 v1, v1, v3, vcc
	v_add_co_u32_e32 v0, vcc, v0, v194
	s_nop 1
	v_addc_co_u32_e32 v1, vcc, 0, v1, vcc
	global_load_dwordx4 v[100:103], v[0:1], off
	v_add_u32_e32 v194, 0x4000, v194
	v_add_u32_e32 v195, 4, v192
	v_cmp_gt_u32_e32 vcc, 0x1000, v195
	v_mov_b32_e32 v0, s98
	v_mov_b32_e32 v1, s99
	v_mov_b32_e32 v3, s58
	v_cndmask_b32_e32 v0, v0, v3, vcc
	v_mov_b32_e32 v3, s59
	v_cndmask_b32_e32 v1, v1, v3, vcc
	v_add_co_u32_e32 v0, vcc, v0, v194
	s_nop 1
	v_addc_co_u32_e32 v1, vcc, 0, v1, vcc
	global_load_dwordx4 v[104:107], v[0:1], off
	v_add_u32_e32 v194, 0x4000, v194
	v_add_u32_e32 v195, 8, v192
	v_cmp_gt_u32_e32 vcc, 0x1000, v195
	v_mov_b32_e32 v0, s98
	v_mov_b32_e32 v1, s99
	v_mov_b32_e32 v3, s58
	v_cndmask_b32_e32 v0, v0, v3, vcc
	v_mov_b32_e32 v3, s59
	v_cndmask_b32_e32 v1, v1, v3, vcc
	v_add_co_u32_e32 v0, vcc, v0, v194
	s_nop 1
	v_addc_co_u32_e32 v1, vcc, 0, v1, vcc
	global_load_dwordx4 v[108:111], v[0:1], off
	v_add_u32_e32 v194, 0x4000, v194
	v_add_u32_e32 v195, 12, v192
	v_cmp_gt_u32_e32 vcc, 0x1000, v195
	v_mov_b32_e32 v0, s98
	v_mov_b32_e32 v1, s99
	v_mov_b32_e32 v3, s58
	v_cndmask_b32_e32 v0, v0, v3, vcc
	v_mov_b32_e32 v3, s59
	v_cndmask_b32_e32 v1, v1, v3, vcc
	v_add_co_u32_e32 v0, vcc, v0, v194
	s_nop 1
	v_addc_co_u32_e32 v1, vcc, 0, v1, vcc
	global_load_dwordx4 v[112:115], v[0:1], off
	v_add_u32_e32 v194, 0x4000, v194
	v_add_u32_e32 v195, 16, v192
	v_cmp_gt_u32_e32 vcc, 0x1000, v195
	v_mov_b32_e32 v0, s98
	v_mov_b32_e32 v1, s99
	v_mov_b32_e32 v3, s58
	v_cndmask_b32_e32 v0, v0, v3, vcc
	v_mov_b32_e32 v3, s59
	v_cndmask_b32_e32 v1, v1, v3, vcc
	v_add_co_u32_e32 v0, vcc, v0, v194
	s_nop 1
	v_addc_co_u32_e32 v1, vcc, 0, v1, vcc
	global_load_dwordx4 v[116:119], v[0:1], off
	v_add_u32_e32 v194, 0x4000, v194
	v_add_u32_e32 v195, 20, v192
	v_cmp_gt_u32_e32 vcc, 0x1000, v195
	v_mov_b32_e32 v0, s98
	v_mov_b32_e32 v1, s99
	v_mov_b32_e32 v3, s58
	v_cndmask_b32_e32 v0, v0, v3, vcc
	v_mov_b32_e32 v3, s59
	v_cndmask_b32_e32 v1, v1, v3, vcc
	v_add_co_u32_e32 v0, vcc, v0, v194
	s_nop 1
	v_addc_co_u32_e32 v1, vcc, 0, v1, vcc
	global_load_dwordx4 v[120:123], v[0:1], off
	v_add_u32_e32 v194, 0x4000, v194
	v_add_u32_e32 v195, 24, v192
	v_cmp_gt_u32_e32 vcc, 0x1000, v195
	v_mov_b32_e32 v0, s98
	v_mov_b32_e32 v1, s99
	v_mov_b32_e32 v3, s58
	v_cndmask_b32_e32 v0, v0, v3, vcc
	v_mov_b32_e32 v3, s59
	v_cndmask_b32_e32 v1, v1, v3, vcc
	v_add_co_u32_e32 v0, vcc, v0, v194
	s_nop 1
	v_addc_co_u32_e32 v1, vcc, 0, v1, vcc
	global_load_dwordx4 v[124:127], v[0:1], off
	v_add_u32_e32 v194, 0x4000, v194
	v_add_u32_e32 v195, 28, v192
	v_cmp_gt_u32_e32 vcc, 0x1000, v195
	v_mov_b32_e32 v0, s98
	v_mov_b32_e32 v1, s99
	v_mov_b32_e32 v3, s58
	v_cndmask_b32_e32 v0, v0, v3, vcc
	v_mov_b32_e32 v3, s59
	v_cndmask_b32_e32 v1, v1, v3, vcc
	v_add_co_u32_e32 v0, vcc, v0, v194
	s_nop 1
	v_addc_co_u32_e32 v1, vcc, 0, v1, vcc
	global_load_dwordx4 v[128:131], v[0:1], off
	v_add_u32_e32 v194, 0x4000, v194
	v_add_u32_e32 v195, 32, v192
	v_cmp_gt_u32_e32 vcc, 0x1000, v195
	v_mov_b32_e32 v0, s98
	v_mov_b32_e32 v1, s99
	v_mov_b32_e32 v3, s58
	v_cndmask_b32_e32 v0, v0, v3, vcc
	v_mov_b32_e32 v3, s59
	v_cndmask_b32_e32 v1, v1, v3, vcc
	v_add_co_u32_e32 v0, vcc, v0, v194
	s_nop 1
	v_addc_co_u32_e32 v1, vcc, 0, v1, vcc
	global_load_dwordx4 v[132:135], v[0:1], off
	v_add_u32_e32 v194, 0x4000, v194
	v_add_u32_e32 v195, 36, v192
	v_cmp_gt_u32_e32 vcc, 0x1000, v195
	v_mov_b32_e32 v0, s98
	v_mov_b32_e32 v1, s99
	v_mov_b32_e32 v3, s58
	v_cndmask_b32_e32 v0, v0, v3, vcc
	v_mov_b32_e32 v3, s59
	v_cndmask_b32_e32 v1, v1, v3, vcc
	v_add_co_u32_e32 v0, vcc, v0, v194
	s_nop 1
	v_addc_co_u32_e32 v1, vcc, 0, v1, vcc
	global_load_dwordx4 v[136:139], v[0:1], off
	v_add_u32_e32 v194, 0x4000, v194
	v_add_u32_e32 v195, 40, v192
	v_cmp_gt_u32_e32 vcc, 0x1000, v195
	v_mov_b32_e32 v0, s98
	v_mov_b32_e32 v1, s99
	v_mov_b32_e32 v3, s58
	v_cndmask_b32_e32 v0, v0, v3, vcc
	v_mov_b32_e32 v3, s59
	v_cndmask_b32_e32 v1, v1, v3, vcc
	v_add_co_u32_e32 v0, vcc, v0, v194
	s_nop 1
	v_addc_co_u32_e32 v1, vcc, 0, v1, vcc
	global_load_dwordx4 v[140:143], v[0:1], off
	v_add_u32_e32 v194, 0x4000, v194
	v_add_u32_e32 v195, 44, v192
	v_cmp_gt_u32_e32 vcc, 0x1000, v195
	v_mov_b32_e32 v0, s98
	v_mov_b32_e32 v1, s99
	v_mov_b32_e32 v3, s58
	v_cndmask_b32_e32 v0, v0, v3, vcc
	v_mov_b32_e32 v3, s59
	v_cndmask_b32_e32 v1, v1, v3, vcc
	v_add_co_u32_e32 v0, vcc, v0, v194
	s_nop 1
	v_addc_co_u32_e32 v1, vcc, 0, v1, vcc
	global_load_dwordx4 v[144:147], v[0:1], off
	v_add_u32_e32 v194, 0x4000, v194
	v_add_u32_e32 v195, s4, v193
	global_load_dwordx4 v[148:151], v195, s[100:101]
	v_add_u32_e32 v195, s5, v193
	global_load_dwordx4 v[152:155], v195, s[100:101]
	ds_write_b32 v203, v4 offset:0
	ds_write_b32 v203, v5 offset:272
	ds_write_b32 v203, v6 offset:544
	ds_write_b32 v203, v7 offset:816
	ds_write_b32 v203, v8 offset:64
	ds_write_b32 v203, v9 offset:336
	ds_write_b32 v203, v10 offset:608
	ds_write_b32 v203, v11 offset:880
	ds_write_b32 v203, v12 offset:128
	ds_write_b32 v203, v13 offset:400
	ds_write_b32 v203, v14 offset:672
	ds_write_b32 v203, v15 offset:944
	ds_write_b32 v203, v16 offset:192
	ds_write_b32 v203, v17 offset:464
	ds_write_b32 v203, v18 offset:736
	ds_write_b32 v203, v19 offset:1008
	s_waitcnt lgkmcnt(0)
	ds_read_b128 v[156:159], v204 offset:0
	ds_read_b128 v[160:163], v204 offset:1088
	ds_read_b128 v[164:167], v204 offset:2176
	ds_read_b128 v[168:171], v204 offset:3264
	s_waitcnt lgkmcnt(0)
	v_add_u32_e32 v195, 48, v192
	v_cmp_gt_u32_e32 vcc, 0x1000, v195
	v_mov_b32_e32 v0, s98
	v_mov_b32_e32 v1, s99
	v_mov_b32_e32 v3, s58
	v_cndmask_b32_e32 v0, v0, v3, vcc
	v_mov_b32_e32 v3, s59
	v_cndmask_b32_e32 v1, v1, v3, vcc
	v_add_co_u32_e32 v0, vcc, v0, v194
	s_nop 1
	v_addc_co_u32_e32 v1, vcc, 0, v1, vcc
	global_load_dwordx4 v[4:7], v[0:1], off
	v_add_u32_e32 v194, 0x4000, v194
	v_add_u32_e32 v195, 52, v192
	v_cmp_gt_u32_e32 vcc, 0x1000, v195
	v_mov_b32_e32 v0, s98
	v_mov_b32_e32 v1, s99
	v_mov_b32_e32 v3, s58
	v_cndmask_b32_e32 v0, v0, v3, vcc
	v_mov_b32_e32 v3, s59
	v_cndmask_b32_e32 v1, v1, v3, vcc
	v_add_co_u32_e32 v0, vcc, v0, v194
	s_nop 1
	v_addc_co_u32_e32 v1, vcc, 0, v1, vcc
	global_load_dwordx4 v[8:11], v[0:1], off
	v_add_u32_e32 v194, 0x4000, v194
	v_add_u32_e32 v195, 56, v192
	v_cmp_gt_u32_e32 vcc, 0x1000, v195
	v_mov_b32_e32 v0, s98
	v_mov_b32_e32 v1, s99
	v_mov_b32_e32 v3, s58
	v_cndmask_b32_e32 v0, v0, v3, vcc
	v_mov_b32_e32 v3, s59
	v_cndmask_b32_e32 v1, v1, v3, vcc
	v_add_co_u32_e32 v0, vcc, v0, v194
	s_nop 1
	v_addc_co_u32_e32 v1, vcc, 0, v1, vcc
	global_load_dwordx4 v[12:15], v[0:1], off
	v_add_u32_e32 v194, 0x4000, v194
	v_add_u32_e32 v195, 60, v192
	v_cmp_gt_u32_e32 vcc, 0x1000, v195
	v_mov_b32_e32 v0, s98
	v_mov_b32_e32 v1, s99
	v_mov_b32_e32 v3, s58
	v_cndmask_b32_e32 v0, v0, v3, vcc
	v_mov_b32_e32 v3, s59
	v_cndmask_b32_e32 v1, v1, v3, vcc
	v_add_co_u32_e32 v0, vcc, v0, v194
	s_nop 1
	v_addc_co_u32_e32 v1, vcc, 0, v1, vcc
	global_load_dwordx4 v[16:19], v[0:1], off
	v_add_u32_e32 v194, 0x4000, v194
	v_add_u32_e32 v195, 0, v192
	v_cmp_le_u32_e32 vcc, s7, v195
	s_waitcnt vmcnt(4)
	v_cndmask_b32_e32 v172, v148, v152, vcc
	v_cndmask_b32_e32 v173, v149, v153, vcc
	v_cndmask_b32_e32 v174, v150, v154, vcc
	v_cndmask_b32_e32 v175, v151, v155, vcc
	v_fmac_f32_e32 v100, v172, v156
	v_fmac_f32_e32 v101, v173, v157
	v_fmac_f32_e32 v102, v174, v158
	v_fmac_f32_e32 v103, v175, v159
	global_store_dwordx4 v197, v[100:103], s[56:57] sc0 sc1
	v_add_u32_e32 v197, 0x4000, v197
	v_add_u32_e32 v195, 4, v192
	v_cmp_le_u32_e32 vcc, s7, v195
	s_waitcnt vmcnt(5)
	s_waitcnt lgkmcnt(2)
	v_cndmask_b32_e32 v172, v148, v152, vcc
	v_cndmask_b32_e32 v173, v149, v153, vcc
	v_cndmask_b32_e32 v174, v150, v154, vcc
	v_cndmask_b32_e32 v175, v151, v155, vcc
	v_fmac_f32_e32 v104, v172, v160
	v_fmac_f32_e32 v105, v173, v161
	v_fmac_f32_e32 v106, v174, v162
	v_fmac_f32_e32 v107, v175, v163
	global_store_dwordx4 v197, v[104:107], s[56:57] sc0 sc1
	v_add_u32_e32 v197, 0x4000, v197
	v_add_u32_e32 v195, 8, v192
	v_cmp_le_u32_e32 vcc, s7, v195
	s_waitcnt vmcnt(6)
	s_waitcnt lgkmcnt(1)
	v_cndmask_b32_e32 v172, v148, v152, vcc
	v_cndmask_b32_e32 v173, v149, v153, vcc
	v_cndmask_b32_e32 v174, v150, v154, vcc
	v_cndmask_b32_e32 v175, v151, v155, vcc
	v_fmac_f32_e32 v108, v172, v164
	v_fmac_f32_e32 v109, v173, v165
	v_fmac_f32_e32 v110, v174, v166
	v_fmac_f32_e32 v111, v175, v167
	global_store_dwordx4 v197, v[108:111], s[56:57] sc0 sc1
	v_add_u32_e32 v197, 0x4000, v197
	v_add_u32_e32 v195, 12, v192
	v_cmp_le_u32_e32 vcc, s7, v195
	s_waitcnt vmcnt(7)
	s_waitcnt lgkmcnt(0)
	v_cndmask_b32_e32 v172, v148, v152, vcc
	v_cndmask_b32_e32 v173, v149, v153, vcc
	v_cndmask_b32_e32 v174, v150, v154, vcc
	v_cndmask_b32_e32 v175, v151, v155, vcc
	v_fmac_f32_e32 v112, v172, v168
	v_fmac_f32_e32 v113, v173, v169
	v_fmac_f32_e32 v114, v174, v170
	v_fmac_f32_e32 v115, v175, v171
	global_store_dwordx4 v197, v[112:115], s[56:57] sc0 sc1
	v_add_u32_e32 v197, 0x4000, v197
	ds_write_b32 v203, v20 offset:0
	ds_write_b32 v203, v21 offset:272
	ds_write_b32 v203, v22 offset:544
	ds_write_b32 v203, v23 offset:816
	ds_write_b32 v203, v24 offset:64
	ds_write_b32 v203, v25 offset:336
	ds_write_b32 v203, v26 offset:608
	ds_write_b32 v203, v27 offset:880
	ds_write_b32 v203, v28 offset:128
	ds_write_b32 v203, v29 offset:400
	ds_write_b32 v203, v30 offset:672
	ds_write_b32 v203, v31 offset:944
	ds_write_b32 v203, v32 offset:192
	ds_write_b32 v203, v33 offset:464
	ds_write_b32 v203, v34 offset:736
	ds_write_b32 v203, v35 offset:1008
	s_waitcnt lgkmcnt(0)
	ds_read_b128 v[156:159], v204 offset:0
	ds_read_b128 v[160:163], v204 offset:1088
	ds_read_b128 v[164:167], v204 offset:2176
	ds_read_b128 v[168:171], v204 offset:3264
	s_waitcnt lgkmcnt(0)
	v_add_u32_e32 v195, 64, v192
	v_cmp_gt_u32_e32 vcc, 0x1000, v195
	v_mov_b32_e32 v0, s98
	v_mov_b32_e32 v1, s99
	v_mov_b32_e32 v3, s58
	v_cndmask_b32_e32 v0, v0, v3, vcc
	v_mov_b32_e32 v3, s59
	v_cndmask_b32_e32 v1, v1, v3, vcc
	v_add_co_u32_e32 v0, vcc, v0, v194
	s_nop 1
	v_addc_co_u32_e32 v1, vcc, 0, v1, vcc
	global_load_dwordx4 v[20:23], v[0:1], off
	v_add_u32_e32 v194, 0x4000, v194
	v_add_u32_e32 v195, 68, v192
	v_cmp_gt_u32_e32 vcc, 0x1000, v195
	v_mov_b32_e32 v0, s98
	v_mov_b32_e32 v1, s99
	v_mov_b32_e32 v3, s58
	v_cndmask_b32_e32 v0, v0, v3, vcc
	v_mov_b32_e32 v3, s59
	v_cndmask_b32_e32 v1, v1, v3, vcc
	v_add_co_u32_e32 v0, vcc, v0, v194
	s_nop 1
	v_addc_co_u32_e32 v1, vcc, 0, v1, vcc
	global_load_dwordx4 v[24:27], v[0:1], off
	v_add_u32_e32 v194, 0x4000, v194
	v_add_u32_e32 v195, 72, v192
	v_cmp_gt_u32_e32 vcc, 0x1000, v195
	v_mov_b32_e32 v0, s98
	v_mov_b32_e32 v1, s99
	v_mov_b32_e32 v3, s58
	v_cndmask_b32_e32 v0, v0, v3, vcc
	v_mov_b32_e32 v3, s59
	v_cndmask_b32_e32 v1, v1, v3, vcc
	v_add_co_u32_e32 v0, vcc, v0, v194
	s_nop 1
	v_addc_co_u32_e32 v1, vcc, 0, v1, vcc
	global_load_dwordx4 v[28:31], v[0:1], off
	v_add_u32_e32 v194, 0x4000, v194
	v_add_u32_e32 v195, 76, v192
	v_cmp_gt_u32_e32 vcc, 0x1000, v195
	v_mov_b32_e32 v0, s98
	v_mov_b32_e32 v1, s99
	v_mov_b32_e32 v3, s58
	v_cndmask_b32_e32 v0, v0, v3, vcc
	v_mov_b32_e32 v3, s59
	v_cndmask_b32_e32 v1, v1, v3, vcc
	v_add_co_u32_e32 v0, vcc, v0, v194
	s_nop 1
	v_addc_co_u32_e32 v1, vcc, 0, v1, vcc
	global_load_dwordx4 v[32:35], v[0:1], off
	v_add_u32_e32 v194, 0x4000, v194
	v_add_u32_e32 v195, 16, v192
	v_cmp_le_u32_e32 vcc, s7, v195
	s_waitcnt vmcnt(12)
	v_cndmask_b32_e32 v172, v148, v152, vcc
	v_cndmask_b32_e32 v173, v149, v153, vcc
	v_cndmask_b32_e32 v174, v150, v154, vcc
	v_cndmask_b32_e32 v175, v151, v155, vcc
	v_fmac_f32_e32 v116, v172, v156
	v_fmac_f32_e32 v117, v173, v157
	v_fmac_f32_e32 v118, v174, v158
	v_fmac_f32_e32 v119, v175, v159
	global_store_dwordx4 v197, v[116:119], s[56:57] sc0 sc1
	v_add_u32_e32 v197, 0x4000, v197
	v_add_u32_e32 v195, 20, v192
	v_cmp_le_u32_e32 vcc, s7, v195
	s_waitcnt vmcnt(13)
	s_waitcnt lgkmcnt(2)
	v_cndmask_b32_e32 v172, v148, v152, vcc
	v_cndmask_b32_e32 v173, v149, v153, vcc
	v_cndmask_b32_e32 v174, v150, v154, vcc
	v_cndmask_b32_e32 v175, v151, v155, vcc
	v_fmac_f32_e32 v120, v172, v160
	v_fmac_f32_e32 v121, v173, v161
	v_fmac_f32_e32 v122, v174, v162
	v_fmac_f32_e32 v123, v175, v163
	global_store_dwordx4 v197, v[120:123], s[56:57] sc0 sc1
	v_add_u32_e32 v197, 0x4000, v197
	v_add_u32_e32 v195, 24, v192
	v_cmp_le_u32_e32 vcc, s7, v195
	s_waitcnt vmcnt(14)
	s_waitcnt lgkmcnt(1)
	v_cndmask_b32_e32 v172, v148, v152, vcc
	v_cndmask_b32_e32 v173, v149, v153, vcc
	v_cndmask_b32_e32 v174, v150, v154, vcc
	v_cndmask_b32_e32 v175, v151, v155, vcc
	v_fmac_f32_e32 v124, v172, v164
	v_fmac_f32_e32 v125, v173, v165
	v_fmac_f32_e32 v126, v174, v166
	v_fmac_f32_e32 v127, v175, v167
	global_store_dwordx4 v197, v[124:127], s[56:57] sc0 sc1
	v_add_u32_e32 v197, 0x4000, v197
	v_add_u32_e32 v195, 28, v192
	v_cmp_le_u32_e32 vcc, s7, v195
	s_waitcnt vmcnt(15)
	s_waitcnt lgkmcnt(0)
	v_cndmask_b32_e32 v172, v148, v152, vcc
	v_cndmask_b32_e32 v173, v149, v153, vcc
	v_cndmask_b32_e32 v174, v150, v154, vcc
	v_cndmask_b32_e32 v175, v151, v155, vcc
	v_fmac_f32_e32 v128, v172, v168
	v_fmac_f32_e32 v129, v173, v169
	v_fmac_f32_e32 v130, v174, v170
	v_fmac_f32_e32 v131, v175, v171
	global_store_dwordx4 v197, v[128:131], s[56:57] sc0 sc1
	v_add_u32_e32 v197, 0x4000, v197
	ds_write_b32 v203, v36 offset:0
	ds_write_b32 v203, v37 offset:272
	ds_write_b32 v203, v38 offset:544
	ds_write_b32 v203, v39 offset:816
	ds_write_b32 v203, v40 offset:64
	ds_write_b32 v203, v41 offset:336
	ds_write_b32 v203, v42 offset:608
	ds_write_b32 v203, v43 offset:880
	ds_write_b32 v203, v44 offset:128
	ds_write_b32 v203, v45 offset:400
	ds_write_b32 v203, v46 offset:672
	ds_write_b32 v203, v47 offset:944
	ds_write_b32 v203, v48 offset:192
	ds_write_b32 v203, v49 offset:464
	ds_write_b32 v203, v50 offset:736
	ds_write_b32 v203, v51 offset:1008
	s_waitcnt lgkmcnt(0)
	ds_read_b128 v[156:159], v204 offset:0
	ds_read_b128 v[160:163], v204 offset:1088
	ds_read_b128 v[164:167], v204 offset:2176
	ds_read_b128 v[168:171], v204 offset:3264
	s_waitcnt lgkmcnt(0)
	v_add_u32_e32 v195, 80, v192
	v_cmp_gt_u32_e32 vcc, 0x1000, v195
	v_mov_b32_e32 v0, s98
	v_mov_b32_e32 v1, s99
	v_mov_b32_e32 v3, s58
	v_cndmask_b32_e32 v0, v0, v3, vcc
	v_mov_b32_e32 v3, s59
	v_cndmask_b32_e32 v1, v1, v3, vcc
	v_add_co_u32_e32 v0, vcc, v0, v194
	s_nop 1
	v_addc_co_u32_e32 v1, vcc, 0, v1, vcc
	global_load_dwordx4 v[36:39], v[0:1], off
	v_add_u32_e32 v194, 0x4000, v194
	v_add_u32_e32 v195, 84, v192
	v_cmp_gt_u32_e32 vcc, 0x1000, v195
	v_mov_b32_e32 v0, s98
	v_mov_b32_e32 v1, s99
	v_mov_b32_e32 v3, s58
	v_cndmask_b32_e32 v0, v0, v3, vcc
	v_mov_b32_e32 v3, s59
	v_cndmask_b32_e32 v1, v1, v3, vcc
	v_add_co_u32_e32 v0, vcc, v0, v194
	s_nop 1
	v_addc_co_u32_e32 v1, vcc, 0, v1, vcc
	global_load_dwordx4 v[40:43], v[0:1], off
	v_add_u32_e32 v194, 0x4000, v194
	v_add_u32_e32 v195, 88, v192
	v_cmp_gt_u32_e32 vcc, 0x1000, v195
	v_mov_b32_e32 v0, s98
	v_mov_b32_e32 v1, s99
	v_mov_b32_e32 v3, s58
	v_cndmask_b32_e32 v0, v0, v3, vcc
	v_mov_b32_e32 v3, s59
	v_cndmask_b32_e32 v1, v1, v3, vcc
	v_add_co_u32_e32 v0, vcc, v0, v194
	s_nop 1
	v_addc_co_u32_e32 v1, vcc, 0, v1, vcc
	global_load_dwordx4 v[44:47], v[0:1], off
	v_add_u32_e32 v194, 0x4000, v194
	v_add_u32_e32 v195, 92, v192
	v_cmp_gt_u32_e32 vcc, 0x1000, v195
	v_mov_b32_e32 v0, s98
	v_mov_b32_e32 v1, s99
	v_mov_b32_e32 v3, s58
	v_cndmask_b32_e32 v0, v0, v3, vcc
	v_mov_b32_e32 v3, s59
	v_cndmask_b32_e32 v1, v1, v3, vcc
	v_add_co_u32_e32 v0, vcc, v0, v194
	s_nop 1
	v_addc_co_u32_e32 v1, vcc, 0, v1, vcc
	global_load_dwordx4 v[48:51], v[0:1], off
	v_add_u32_e32 v194, 0x4000, v194
	v_add_u32_e32 v195, 32, v192
	v_cmp_le_u32_e32 vcc, s7, v195
	s_waitcnt vmcnt(20)
	v_cndmask_b32_e32 v172, v148, v152, vcc
	v_cndmask_b32_e32 v173, v149, v153, vcc
	v_cndmask_b32_e32 v174, v150, v154, vcc
	v_cndmask_b32_e32 v175, v151, v155, vcc
	v_fmac_f32_e32 v132, v172, v156
	v_fmac_f32_e32 v133, v173, v157
	v_fmac_f32_e32 v134, v174, v158
	v_fmac_f32_e32 v135, v175, v159
	global_store_dwordx4 v197, v[132:135], s[56:57] sc0 sc1
	v_add_u32_e32 v197, 0x4000, v197
	v_add_u32_e32 v195, 36, v192
	v_cmp_le_u32_e32 vcc, s7, v195
	s_waitcnt vmcnt(21)
	s_waitcnt lgkmcnt(2)
	v_cndmask_b32_e32 v172, v148, v152, vcc
	v_cndmask_b32_e32 v173, v149, v153, vcc
	v_cndmask_b32_e32 v174, v150, v154, vcc
	v_cndmask_b32_e32 v175, v151, v155, vcc
	v_fmac_f32_e32 v136, v172, v160
	v_fmac_f32_e32 v137, v173, v161
	v_fmac_f32_e32 v138, v174, v162
	v_fmac_f32_e32 v139, v175, v163
	global_store_dwordx4 v197, v[136:139], s[56:57] sc0 sc1
	v_add_u32_e32 v197, 0x4000, v197
	v_add_u32_e32 v195, 40, v192
	v_cmp_le_u32_e32 vcc, s7, v195
	s_waitcnt vmcnt(22)
	s_waitcnt lgkmcnt(1)
	v_cndmask_b32_e32 v172, v148, v152, vcc
	v_cndmask_b32_e32 v173, v149, v153, vcc
	v_cndmask_b32_e32 v174, v150, v154, vcc
	v_cndmask_b32_e32 v175, v151, v155, vcc
	v_fmac_f32_e32 v140, v172, v164
	v_fmac_f32_e32 v141, v173, v165
	v_fmac_f32_e32 v142, v174, v166
	v_fmac_f32_e32 v143, v175, v167
	global_store_dwordx4 v197, v[140:143], s[56:57] sc0 sc1
	v_add_u32_e32 v197, 0x4000, v197
	v_add_u32_e32 v195, 44, v192
	v_cmp_le_u32_e32 vcc, s7, v195
	s_waitcnt vmcnt(23)
	s_waitcnt lgkmcnt(0)
	v_cndmask_b32_e32 v172, v148, v152, vcc
	v_cndmask_b32_e32 v173, v149, v153, vcc
	v_cndmask_b32_e32 v174, v150, v154, vcc
	v_cndmask_b32_e32 v175, v151, v155, vcc
	v_fmac_f32_e32 v144, v172, v168
	v_fmac_f32_e32 v145, v173, v169
	v_fmac_f32_e32 v146, v174, v170
	v_fmac_f32_e32 v147, v175, v171
	global_store_dwordx4 v197, v[144:147], s[56:57] sc0 sc1
	v_add_u32_e32 v197, 0x4000, v197
	ds_write_b32 v203, v52 offset:0
	ds_write_b32 v203, v53 offset:272
	ds_write_b32 v203, v54 offset:544
	ds_write_b32 v203, v55 offset:816
	ds_write_b32 v203, v56 offset:64
	ds_write_b32 v203, v57 offset:336
	ds_write_b32 v203, v58 offset:608
	ds_write_b32 v203, v59 offset:880
	ds_write_b32 v203, v60 offset:128
	ds_write_b32 v203, v61 offset:400
	ds_write_b32 v203, v62 offset:672
	ds_write_b32 v203, v63 offset:944
	ds_write_b32 v203, v64 offset:192
	ds_write_b32 v203, v65 offset:464
	ds_write_b32 v203, v66 offset:736
	ds_write_b32 v203, v67 offset:1008
	s_waitcnt lgkmcnt(0)
	ds_read_b128 v[156:159], v204 offset:0
	ds_read_b128 v[160:163], v204 offset:1088
	ds_read_b128 v[164:167], v204 offset:2176
	ds_read_b128 v[168:171], v204 offset:3264
	v_add_u32_e32 v195, 48, v192
	v_cmp_le_u32_e32 vcc, s7, v195
	s_waitcnt vmcnt(23)
	s_waitcnt lgkmcnt(3)
	v_cndmask_b32_e32 v172, v148, v152, vcc
	v_cndmask_b32_e32 v173, v149, v153, vcc
	v_cndmask_b32_e32 v174, v150, v154, vcc
	v_cndmask_b32_e32 v175, v151, v155, vcc
	v_fmac_f32_e32 v4, v172, v156
	v_fmac_f32_e32 v5, v173, v157
	v_fmac_f32_e32 v6, v174, v158
	v_fmac_f32_e32 v7, v175, v159
	global_store_dwordx4 v197, v[4:7], s[56:57] sc0 sc1
	v_add_u32_e32 v197, 0x4000, v197
	v_add_u32_e32 v195, 52, v192
	v_cmp_le_u32_e32 vcc, s7, v195
	s_waitcnt vmcnt(23)
	s_waitcnt lgkmcnt(2)
	v_cndmask_b32_e32 v172, v148, v152, vcc
	v_cndmask_b32_e32 v173, v149, v153, vcc
	v_cndmask_b32_e32 v174, v150, v154, vcc
	v_cndmask_b32_e32 v175, v151, v155, vcc
	v_fmac_f32_e32 v8, v172, v160
	v_fmac_f32_e32 v9, v173, v161
	v_fmac_f32_e32 v10, v174, v162
	v_fmac_f32_e32 v11, v175, v163
	global_store_dwordx4 v197, v[8:11], s[56:57] sc0 sc1
	v_add_u32_e32 v197, 0x4000, v197
	v_add_u32_e32 v195, 56, v192
	v_cmp_le_u32_e32 vcc, s7, v195
	s_waitcnt vmcnt(23)
	s_waitcnt lgkmcnt(1)
	v_cndmask_b32_e32 v172, v148, v152, vcc
	v_cndmask_b32_e32 v173, v149, v153, vcc
	v_cndmask_b32_e32 v174, v150, v154, vcc
	v_cndmask_b32_e32 v175, v151, v155, vcc
	v_fmac_f32_e32 v12, v172, v164
	v_fmac_f32_e32 v13, v173, v165
	v_fmac_f32_e32 v14, v174, v166
	v_fmac_f32_e32 v15, v175, v167
	global_store_dwordx4 v197, v[12:15], s[56:57] sc0 sc1
	v_add_u32_e32 v197, 0x4000, v197
	v_add_u32_e32 v195, 60, v192
	v_cmp_le_u32_e32 vcc, s7, v195
	s_waitcnt vmcnt(23)
	s_waitcnt lgkmcnt(0)
	v_cndmask_b32_e32 v172, v148, v152, vcc
	v_cndmask_b32_e32 v173, v149, v153, vcc
	v_cndmask_b32_e32 v174, v150, v154, vcc
	v_cndmask_b32_e32 v175, v151, v155, vcc
	v_fmac_f32_e32 v16, v172, v168
	v_fmac_f32_e32 v17, v173, v169
	v_fmac_f32_e32 v18, v174, v170
	v_fmac_f32_e32 v19, v175, v171
	global_store_dwordx4 v197, v[16:19], s[56:57] sc0 sc1
	v_add_u32_e32 v197, 0x4000, v197
	ds_write_b32 v203, v68 offset:0
	ds_write_b32 v203, v69 offset:272
	ds_write_b32 v203, v70 offset:544
	ds_write_b32 v203, v71 offset:816
	ds_write_b32 v203, v72 offset:64
	ds_write_b32 v203, v73 offset:336
	ds_write_b32 v203, v74 offset:608
	ds_write_b32 v203, v75 offset:880
	ds_write_b32 v203, v76 offset:128
	ds_write_b32 v203, v77 offset:400
	ds_write_b32 v203, v78 offset:672
	ds_write_b32 v203, v79 offset:944
	ds_write_b32 v203, v80 offset:192
	ds_write_b32 v203, v81 offset:464
	ds_write_b32 v203, v82 offset:736
	ds_write_b32 v203, v83 offset:1008
	s_waitcnt lgkmcnt(0)
	ds_read_b128 v[156:159], v204 offset:0
	ds_read_b128 v[160:163], v204 offset:1088
	ds_read_b128 v[164:167], v204 offset:2176
	ds_read_b128 v[168:171], v204 offset:3264
	v_add_u32_e32 v195, 64, v192
	v_cmp_le_u32_e32 vcc, s7, v195
	s_waitcnt vmcnt(19)
	s_waitcnt lgkmcnt(3)
	v_cndmask_b32_e32 v172, v148, v152, vcc
	v_cndmask_b32_e32 v173, v149, v153, vcc
	v_cndmask_b32_e32 v174, v150, v154, vcc
	v_cndmask_b32_e32 v175, v151, v155, vcc
	v_fmac_f32_e32 v20, v172, v156
	v_fmac_f32_e32 v21, v173, v157
	v_fmac_f32_e32 v22, v174, v158
	v_fmac_f32_e32 v23, v175, v159
	global_store_dwordx4 v197, v[20:23], s[56:57] sc0 sc1
	v_add_u32_e32 v197, 0x4000, v197
	v_add_u32_e32 v195, 68, v192
	v_cmp_le_u32_e32 vcc, s7, v195
	s_waitcnt vmcnt(19)
	s_waitcnt lgkmcnt(2)
	v_cndmask_b32_e32 v172, v148, v152, vcc
	v_cndmask_b32_e32 v173, v149, v153, vcc
	v_cndmask_b32_e32 v174, v150, v154, vcc
	v_cndmask_b32_e32 v175, v151, v155, vcc
	v_fmac_f32_e32 v24, v172, v160
	v_fmac_f32_e32 v25, v173, v161
	v_fmac_f32_e32 v26, v174, v162
	v_fmac_f32_e32 v27, v175, v163
	global_store_dwordx4 v197, v[24:27], s[56:57] sc0 sc1
	v_add_u32_e32 v197, 0x4000, v197
	v_add_u32_e32 v195, 72, v192
	v_cmp_le_u32_e32 vcc, s7, v195
	s_waitcnt vmcnt(19)
	s_waitcnt lgkmcnt(1)
	v_cndmask_b32_e32 v172, v148, v152, vcc
	v_cndmask_b32_e32 v173, v149, v153, vcc
	v_cndmask_b32_e32 v174, v150, v154, vcc
	v_cndmask_b32_e32 v175, v151, v155, vcc
	v_fmac_f32_e32 v28, v172, v164
	v_fmac_f32_e32 v29, v173, v165
	v_fmac_f32_e32 v30, v174, v166
	v_fmac_f32_e32 v31, v175, v167
	global_store_dwordx4 v197, v[28:31], s[56:57] sc0 sc1
	v_add_u32_e32 v197, 0x4000, v197
	v_add_u32_e32 v195, 76, v192
	v_cmp_le_u32_e32 vcc, s7, v195
	s_waitcnt vmcnt(19)
	s_waitcnt lgkmcnt(0)
	v_cndmask_b32_e32 v172, v148, v152, vcc
	v_cndmask_b32_e32 v173, v149, v153, vcc
	v_cndmask_b32_e32 v174, v150, v154, vcc
	v_cndmask_b32_e32 v175, v151, v155, vcc
	v_fmac_f32_e32 v32, v172, v168
	v_fmac_f32_e32 v33, v173, v169
	v_fmac_f32_e32 v34, v174, v170
	v_fmac_f32_e32 v35, v175, v171
	global_store_dwordx4 v197, v[32:35], s[56:57] sc0 sc1
	v_add_u32_e32 v197, 0x4000, v197
	ds_write_b32 v203, v84 offset:0
	ds_write_b32 v203, v85 offset:272
	ds_write_b32 v203, v86 offset:544
	ds_write_b32 v203, v87 offset:816
	ds_write_b32 v203, v88 offset:64
	ds_write_b32 v203, v89 offset:336
	ds_write_b32 v203, v90 offset:608
	ds_write_b32 v203, v91 offset:880
	ds_write_b32 v203, v92 offset:128
	ds_write_b32 v203, v93 offset:400
	ds_write_b32 v203, v94 offset:672
	ds_write_b32 v203, v95 offset:944
	ds_write_b32 v203, v96 offset:192
	ds_write_b32 v203, v97 offset:464
	ds_write_b32 v203, v98 offset:736
	ds_write_b32 v203, v99 offset:1008
	s_waitcnt lgkmcnt(0)
	ds_read_b128 v[156:159], v204 offset:0
	ds_read_b128 v[160:163], v204 offset:1088
	ds_read_b128 v[164:167], v204 offset:2176
	ds_read_b128 v[168:171], v204 offset:3264
	v_add_u32_e32 v195, 80, v192
	v_cmp_le_u32_e32 vcc, s7, v195
	s_waitcnt vmcnt(15)
	s_waitcnt lgkmcnt(3)
	v_cndmask_b32_e32 v172, v148, v152, vcc
	v_cndmask_b32_e32 v173, v149, v153, vcc
	v_cndmask_b32_e32 v174, v150, v154, vcc
	v_cndmask_b32_e32 v175, v151, v155, vcc
	v_fmac_f32_e32 v36, v172, v156
	v_fmac_f32_e32 v37, v173, v157
	v_fmac_f32_e32 v38, v174, v158
	v_fmac_f32_e32 v39, v175, v159
	global_store_dwordx4 v197, v[36:39], s[56:57] sc0 sc1
	v_add_u32_e32 v197, 0x4000, v197
	v_add_u32_e32 v195, 84, v192
	v_cmp_le_u32_e32 vcc, s7, v195
	s_waitcnt vmcnt(15)
	s_waitcnt lgkmcnt(2)
	v_cndmask_b32_e32 v172, v148, v152, vcc
	v_cndmask_b32_e32 v173, v149, v153, vcc
	v_cndmask_b32_e32 v174, v150, v154, vcc
	v_cndmask_b32_e32 v175, v151, v155, vcc
	v_fmac_f32_e32 v40, v172, v160
	v_fmac_f32_e32 v41, v173, v161
	v_fmac_f32_e32 v42, v174, v162
	v_fmac_f32_e32 v43, v175, v163
	global_store_dwordx4 v197, v[40:43], s[56:57] sc0 sc1
	v_add_u32_e32 v197, 0x4000, v197
	v_add_u32_e32 v195, 88, v192
	v_cmp_le_u32_e32 vcc, s7, v195
	s_waitcnt vmcnt(15)
	s_waitcnt lgkmcnt(1)
	v_cndmask_b32_e32 v172, v148, v152, vcc
	v_cndmask_b32_e32 v173, v149, v153, vcc
	v_cndmask_b32_e32 v174, v150, v154, vcc
	v_cndmask_b32_e32 v175, v151, v155, vcc
	v_fmac_f32_e32 v44, v172, v164
	v_fmac_f32_e32 v45, v173, v165
	v_fmac_f32_e32 v46, v174, v166
	v_fmac_f32_e32 v47, v175, v167
	global_store_dwordx4 v197, v[44:47], s[56:57] sc0 sc1
	v_add_u32_e32 v197, 0x4000, v197
	v_add_u32_e32 v195, 92, v192
	v_cmp_le_u32_e32 vcc, s7, v195
	s_waitcnt vmcnt(15)
	s_waitcnt lgkmcnt(0)
	v_cndmask_b32_e32 v172, v148, v152, vcc
	v_cndmask_b32_e32 v173, v149, v153, vcc
	v_cndmask_b32_e32 v174, v150, v154, vcc
	v_cndmask_b32_e32 v175, v151, v155, vcc
	v_fmac_f32_e32 v48, v172, v168
	v_fmac_f32_e32 v49, v173, v169
	v_fmac_f32_e32 v50, v174, v170
	v_fmac_f32_e32 v51, v175, v171
	global_store_dwordx4 v197, v[48:51], s[56:57] sc0 sc1
	v_add_u32_e32 v197, 0x4000, v197
	v_mov_b32_e32 v4, 0
	v_mov_b32_e32 v5, 0
	v_mov_b32_e32 v6, 0
	v_mov_b32_e32 v7, 0
	v_mov_b32_e32 v8, 0
	v_mov_b32_e32 v9, 0
	v_mov_b32_e32 v10, 0
	v_mov_b32_e32 v11, 0
	v_mov_b32_e32 v12, 0
	v_mov_b32_e32 v13, 0
	v_mov_b32_e32 v14, 0
	v_mov_b32_e32 v15, 0
	v_mov_b32_e32 v16, 0
	v_mov_b32_e32 v17, 0
	v_mov_b32_e32 v18, 0
	v_mov_b32_e32 v19, 0
	v_mov_b32_e32 v20, 0
	v_mov_b32_e32 v21, 0
	v_mov_b32_e32 v22, 0
	v_mov_b32_e32 v23, 0
	v_mov_b32_e32 v24, 0
	v_mov_b32_e32 v25, 0
	v_mov_b32_e32 v26, 0
	v_mov_b32_e32 v27, 0
	v_mov_b32_e32 v28, 0
	v_mov_b32_e32 v29, 0
	v_mov_b32_e32 v30, 0
	v_mov_b32_e32 v31, 0
	v_mov_b32_e32 v32, 0
	v_mov_b32_e32 v33, 0
	v_mov_b32_e32 v34, 0
	v_mov_b32_e32 v35, 0
	v_mov_b32_e32 v36, 0
	v_mov_b32_e32 v37, 0
	v_mov_b32_e32 v38, 0
	v_mov_b32_e32 v39, 0
	v_mov_b32_e32 v40, 0
	v_mov_b32_e32 v41, 0
	v_mov_b32_e32 v42, 0
	v_mov_b32_e32 v43, 0
	v_mov_b32_e32 v44, 0
	v_mov_b32_e32 v45, 0
	v_mov_b32_e32 v46, 0
	v_mov_b32_e32 v47, 0
	v_mov_b32_e32 v48, 0
	v_mov_b32_e32 v49, 0
	v_mov_b32_e32 v50, 0
	v_mov_b32_e32 v51, 0
	v_mov_b32_e32 v52, 0
	v_mov_b32_e32 v53, 0
	v_mov_b32_e32 v54, 0
	v_mov_b32_e32 v55, 0
	v_mov_b32_e32 v56, 0
	v_mov_b32_e32 v57, 0
	v_mov_b32_e32 v58, 0
	v_mov_b32_e32 v59, 0
	v_mov_b32_e32 v60, 0
	v_mov_b32_e32 v61, 0
	v_mov_b32_e32 v62, 0
	v_mov_b32_e32 v63, 0
	v_mov_b32_e32 v64, 0
	v_mov_b32_e32 v65, 0
	v_mov_b32_e32 v66, 0
	v_mov_b32_e32 v67, 0
	v_mov_b32_e32 v68, 0
	v_mov_b32_e32 v69, 0
	v_mov_b32_e32 v70, 0
	v_mov_b32_e32 v71, 0
	v_mov_b32_e32 v72, 0
	v_mov_b32_e32 v73, 0
	v_mov_b32_e32 v74, 0
	v_mov_b32_e32 v75, 0
	v_mov_b32_e32 v76, 0
	v_mov_b32_e32 v77, 0
	v_mov_b32_e32 v78, 0
	v_mov_b32_e32 v79, 0
	v_mov_b32_e32 v80, 0
	v_mov_b32_e32 v81, 0
	v_mov_b32_e32 v82, 0
	v_mov_b32_e32 v83, 0
	v_mov_b32_e32 v84, 0
	v_mov_b32_e32 v85, 0
	v_mov_b32_e32 v86, 0
	v_mov_b32_e32 v87, 0
	v_mov_b32_e32 v88, 0
	v_mov_b32_e32 v89, 0
	v_mov_b32_e32 v90, 0
	v_mov_b32_e32 v91, 0
	v_mov_b32_e32 v92, 0
	v_mov_b32_e32 v93, 0
	v_mov_b32_e32 v94, 0
	v_mov_b32_e32 v95, 0
	v_mov_b32_e32 v96, 0
	v_mov_b32_e32 v97, 0
	v_mov_b32_e32 v98, 0
	v_mov_b32_e32 v99, 0
	s_mov_b32 s34, 0
	s_add_u32 s35, s35, s52
	s_cmp_ge_u32 s31, s30
	s_cbranch_scc1 .Lgm_wo_exit
